# non-temporal hint also on branch-merge, out-proj and ffn-out epilogue stores
# baseline (speedup 1.0000x reference)
; __device__ __forceinline__ unsigned cvt_pk_bf16(float lo, float hi) { unsigned r; asm volatile("v_cvt_pk_bf16_f32 %0, %1, %2" : "=v"(r) : "v"(lo), "v"(hi)); return r; }
;     __device__ __forceinline__ void operator()(const f32x4 (&acc)[2][2][4][2], const pg8::Unit& u, int wr, int wc, int fr, int fq, LAS unsigned char*) const {
;     ...
;                 const int row = row0 + ai * 128 + m * 16; const size_t off = (size_t)row * DM + col0; float q = 0.f;
; #pragma unroll
;                 for (int bj = 0; bj < 2; ++bj)
; #pragma unroll
;                     for (int n = 0; n < 2; ++n) { const size_t o = off + bj * 128 + n * 16; const f32x4 xv = *(const f32x4*)(xin + o) + acc[ai][bj][m][n]; *(f32x4*)(xout + o) = xv;
;                         q += (xv[0] * xv[0] + xv[1] * xv[1]) + (xv[2] * xv[2] + xv[3] * xv[3]);
;                         u32x2 w; w.x = cvt_pk_bf16(xv[0], xv[1]); w.y = cvt_pk_bf16(xv[2], xv[3]); *(u32x2*)(xb + o) = w; }
;                 q += __shfl_xor(q, 16); q += __shfl_xor(q, 32);
;                 if (fq == 0) ssq[(size_t)row * 16 + u.pn * 4 + wc] = q;
.LBB0_64:
	v_lshl_add_u32 v136, s62, 8, v142
	v_lshl_or_b32 v137, s60, 8, v144
	s_lshl_b32 s26, s60, 4
	s_lshl_b32 s27, s81, 2
	s_add_u32 s26, s26, s27
	v_lshl_add_u32 v139, v136, 10, v137
	v_lshl_add_u32 v140, v136, 6, s26
	v_lshlrev_b32_e32 v138, 2, v139
	v_lshlrev_b32_e32 v139, 1, v139
	v_xor_b32_e32 v141, 16, v187
	v_xor_b32_e32 v172, 32, v187
	v_lshlrev_b32_e32 v141, 2, v141
	v_lshlrev_b32_e32 v172, 2, v172
	global_load_dwordx4 v[198:201], v138, s[18:19]
	global_load_dwordx4 v[202:205], v138, s[18:19] offset:64
	global_load_dwordx4 v[206:209], v138, s[18:19] offset:512
	global_load_dwordx4 v[210:213], v138, s[18:19] offset:576
	v_add_u32_e32 v173, 0x10000, v138
	global_load_dwordx4 v[214:217], v173, s[18:19]
	global_load_dwordx4 v[218:221], v173, s[18:19] offset:64
	global_load_dwordx4 v[222:225], v173, s[18:19] offset:512
	global_load_dwordx4 v[226:229], v173, s[18:19] offset:576
	v_add_u32_e32 v173, 0x20000, v138
	global_load_dwordx4 v[156:159], v173, s[18:19]
	global_load_dwordx4 v[160:163], v173, s[18:19] offset:64
	global_load_dwordx4 v[164:167], v173, s[18:19] offset:512
	global_load_dwordx4 v[168:171], v173, s[18:19] offset:576
	v_mov_b32_e32 v174, v138
	v_mov_b32_e32 v175, v139
	v_mov_b32_e32 v176, v140
	s_waitcnt vmcnt(11)
	v_pk_add_f32 v[200:201], v[128:129], v[200:201]
	v_pk_add_f32 v[198:199], v[126:127], v[198:199]
	global_store_dwordx4 v174, v[198:201], s[12:13] nt
	v_mul_f32_e32 v178, v201, v201
	v_mul_f32_e32 v177, v199, v199
	v_fmac_f32_e32 v177, v198, v198
	v_fmac_f32_e32 v178, v200, v200
	v_cvt_pk_bf16_f32 v180, v198, v199
	v_cvt_pk_bf16_f32 v181, v200, v201
	v_add_f32_e32 v179, v177, v178
	global_store_dwordx2 v175, v[180:181], s[48:49] nt
	s_waitcnt vmcnt(12)
	v_pk_add_f32 v[204:205], v[124:125], v[204:205]
	v_pk_add_f32 v[202:203], v[122:123], v[202:203]
	global_store_dwordx4 v174, v[202:205], s[12:13] offset:64 nt
	v_mul_f32_e32 v178, v205, v205
	v_mul_f32_e32 v177, v203, v203
	v_fmac_f32_e32 v177, v202, v202
	v_fmac_f32_e32 v178, v204, v204
	v_cvt_pk_bf16_f32 v182, v202, v203
	v_cvt_pk_bf16_f32 v183, v204, v205
	v_add_f32_e32 v177, v177, v178
	v_add_f32_e32 v179, v179, v177
	global_store_dwordx2 v175, v[182:183], s[48:49] offset:32 nt
	s_waitcnt vmcnt(13)
	v_pk_add_f32 v[208:209], v[120:121], v[208:209]
	v_pk_add_f32 v[206:207], v[118:119], v[206:207]
	global_store_dwordx4 v174, v[206:209], s[12:13] offset:512 nt
	v_mul_f32_e32 v178, v209, v209
	v_mul_f32_e32 v177, v207, v207
	v_fmac_f32_e32 v177, v206, v206
	v_fmac_f32_e32 v178, v208, v208
	v_cvt_pk_bf16_f32 v180, v206, v207
	v_cvt_pk_bf16_f32 v181, v208, v209
	v_add_f32_e32 v177, v177, v178
	v_add_f32_e32 v179, v179, v177
	global_store_dwordx2 v175, v[180:181], s[48:49] offset:256 nt
	s_waitcnt vmcnt(14)
	v_pk_add_f32 v[212:213], v[116:117], v[212:213]
	v_pk_add_f32 v[210:211], v[114:115], v[210:211]
	global_store_dwordx4 v174, v[210:213], s[12:13] offset:576 nt
	v_mul_f32_e32 v178, v213, v213
	v_mul_f32_e32 v177, v211, v211
	v_fmac_f32_e32 v177, v210, v210
	v_fmac_f32_e32 v178, v212, v212
	v_cvt_pk_bf16_f32 v182, v210, v211
	v_cvt_pk_bf16_f32 v183, v212, v213
	v_add_f32_e32 v177, v177, v178
	v_add_f32_e32 v179, v179, v177
	global_store_dwordx2 v175, v[182:183], s[48:49] offset:288 nt
	ds_bpermute_b32 v177, v141, v179
	s_waitcnt lgkmcnt(0)
	v_add_f32_e32 v179, v179, v177
	ds_bpermute_b32 v178, v172, v179
	s_waitcnt lgkmcnt(0)
	v_add_f32_e32 v179, v179, v178
	s_and_saveexec_b64 s[62:63], s[4:5]
	global_store_dword v176, v179, s[14:15]
	s_mov_b64 exec, s[62:63]
	v_add_u32_e32 v173, 0x30000, v138
	global_load_dwordx4 v[198:201], v173, s[18:19]
	global_load_dwordx4 v[202:205], v173, s[18:19] offset:64
	global_load_dwordx4 v[206:209], v173, s[18:19] offset:512
	global_load_dwordx4 v[210:213], v173, s[18:19] offset:576
	v_add_u32_e32 v174, 0x10000, v138
	v_add_u32_e32 v175, 0x8000, v139
	v_add_u32_e32 v176, 0x400, v140
	s_waitcnt vmcnt(20)
	v_pk_add_f32 v[216:217], v[112:113], v[216:217]
	v_pk_add_f32 v[214:215], v[110:111], v[214:215]
	global_store_dwordx4 v174, v[214:217], s[12:13] nt
	v_mul_f32_e32 v178, v217, v217
	v_mul_f32_e32 v177, v215, v215
	v_fmac_f32_e32 v177, v214, v214
	v_fmac_f32_e32 v178, v216, v216
	v_cvt_pk_bf16_f32 v180, v214, v215
	v_cvt_pk_bf16_f32 v181, v216, v217
	v_add_f32_e32 v179, v177, v178
	global_store_dwordx2 v175, v[180:181], s[48:49] nt
	s_waitcnt vmcnt(21)
	v_pk_add_f32 v[220:221], v[108:109], v[220:221]
	v_pk_add_f32 v[218:219], v[106:107], v[218:219]
	global_store_dwordx4 v174, v[218:221], s[12:13] offset:64 nt
	v_mul_f32_e32 v178, v221, v221
	v_mul_f32_e32 v177, v219, v219
	v_fmac_f32_e32 v177, v218, v218
	v_fmac_f32_e32 v178, v220, v220
	v_cvt_pk_bf16_f32 v182, v218, v219
	v_cvt_pk_bf16_f32 v183, v220, v221
	v_add_f32_e32 v177, v177, v178
	v_add_f32_e32 v179, v179, v177
	global_store_dwordx2 v175, v[182:183], s[48:49] offset:32 nt
	s_waitcnt vmcnt(22)
	v_pk_add_f32 v[224:225], v[104:105], v[224:225]
	v_pk_add_f32 v[222:223], v[102:103], v[222:223]
	global_store_dwordx4 v174, v[222:225], s[12:13] offset:512 nt
	v_mul_f32_e32 v178, v225, v225
	v_mul_f32_e32 v177, v223, v223
	v_fmac_f32_e32 v177, v222, v222
	v_fmac_f32_e32 v178, v224, v224
	v_cvt_pk_bf16_f32 v180, v222, v223
	v_cvt_pk_bf16_f32 v181, v224, v225
	v_add_f32_e32 v177, v177, v178
	v_add_f32_e32 v179, v179, v177
	global_store_dwordx2 v175, v[180:181], s[48:49] offset:256 nt
	s_waitcnt vmcnt(23)
	v_pk_add_f32 v[228:229], v[100:101], v[228:229]
	v_pk_add_f32 v[226:227], v[98:99], v[226:227]
	global_store_dwordx4 v174, v[226:229], s[12:13] offset:576 nt
	v_mul_f32_e32 v178, v229, v229
	v_mul_f32_e32 v177, v227, v227
	v_fmac_f32_e32 v177, v226, v226
	v_fmac_f32_e32 v178, v228, v228
	v_cvt_pk_bf16_f32 v182, v226, v227
	v_cvt_pk_bf16_f32 v183, v228, v229
	v_add_f32_e32 v177, v177, v178
	v_add_f32_e32 v179, v179, v177
	global_store_dwordx2 v175, v[182:183], s[48:49] offset:288 nt
	ds_bpermute_b32 v177, v141, v179
	s_waitcnt lgkmcnt(0)
; __device__ __forceinline__ unsigned cvt_pk_bf16(float lo, float hi) { unsigned r; asm volatile("v_cvt_pk_bf16_f32 %0, %1, %2" : "=v"(r) : "v"(lo), "v"(hi)); return r; }
;     __device__ __forceinline__ void operator()(const f32x4 (&acc)[2][2][4][2], const pg8::Unit& u, int wr, int wc, int fr, int fq, LAS unsigned char*) const {
;     ...
;                 const int row = row0 + ai * 128 + m * 16; const size_t off = (size_t)row * DM + col0; float q = 0.f;
; #pragma unroll
;                 for (int bj = 0; bj < 2; ++bj)
; #pragma unroll
;                     for (int n = 0; n < 2; ++n) { const size_t o = off + bj * 128 + n * 16; const f32x4 xv = *(const f32x4*)(xin + o) + acc[ai][bj][m][n]; *(f32x4*)(xout + o) = xv;
;                         q += (xv[0] * xv[0] + xv[1] * xv[1]) + (xv[2] * xv[2] + xv[3] * xv[3]);
;                         u32x2 w; w.x = cvt_pk_bf16(xv[0], xv[1]); w.y = cvt_pk_bf16(xv[2], xv[3]); *(u32x2*)(xb + o) = w; }
;                 q += __shfl_xor(q, 16); q += __shfl_xor(q, 32);
;                 if (fq == 0) ssq[(size_t)row * 16 + u.pn * 4 + wc] = q;
	v_add_f32_e32 v179, v179, v177
	ds_bpermute_b32 v178, v172, v179
	s_waitcnt lgkmcnt(0)
	v_add_f32_e32 v179, v179, v178
	s_and_saveexec_b64 s[62:63], s[4:5]
	global_store_dword v176, v179, s[14:15]
	s_mov_b64 exec, s[62:63]
	v_add_u32_e32 v173, 0x80000, v138
	global_load_dwordx4 v[214:217], v173, s[18:19]
	global_load_dwordx4 v[218:221], v173, s[18:19] offset:64
	global_load_dwordx4 v[222:225], v173, s[18:19] offset:512
	global_load_dwordx4 v[226:229], v173, s[18:19] offset:576
	v_add_u32_e32 v174, 0x20000, v138
	v_add_u32_e32 v175, 0x10000, v139
	v_add_u32_e32 v176, 0x800, v140
	s_waitcnt vmcnt(29)
	v_pk_add_f32 v[158:159], v[96:97], v[158:159]
	v_pk_add_f32 v[156:157], v[94:95], v[156:157]
	global_store_dwordx4 v174, v[156:159], s[12:13] nt
	v_mul_f32_e32 v178, v159, v159
	v_mul_f32_e32 v177, v157, v157
	v_fmac_f32_e32 v177, v156, v156
	v_fmac_f32_e32 v178, v158, v158
	v_cvt_pk_bf16_f32 v180, v156, v157
	v_cvt_pk_bf16_f32 v181, v158, v159
	v_add_f32_e32 v179, v177, v178
	global_store_dwordx2 v175, v[180:181], s[48:49] nt
	s_waitcnt vmcnt(30)
	v_pk_add_f32 v[162:163], v[92:93], v[162:163]
	v_pk_add_f32 v[160:161], v[90:91], v[160:161]
	global_store_dwordx4 v174, v[160:163], s[12:13] offset:64 nt
	v_mul_f32_e32 v178, v163, v163
	v_mul_f32_e32 v177, v161, v161
	v_fmac_f32_e32 v177, v160, v160
	v_fmac_f32_e32 v178, v162, v162
	v_cvt_pk_bf16_f32 v182, v160, v161
	v_cvt_pk_bf16_f32 v183, v162, v163
	v_add_f32_e32 v177, v177, v178
	v_add_f32_e32 v179, v179, v177
	global_store_dwordx2 v175, v[182:183], s[48:49] offset:32 nt
	s_waitcnt vmcnt(31)
	v_pk_add_f32 v[166:167], v[88:89], v[166:167]
	v_pk_add_f32 v[164:165], v[86:87], v[164:165]
	global_store_dwordx4 v174, v[164:167], s[12:13] offset:512 nt
	v_mul_f32_e32 v178, v167, v167
	v_mul_f32_e32 v177, v165, v165
	v_fmac_f32_e32 v177, v164, v164
	v_fmac_f32_e32 v178, v166, v166
	v_cvt_pk_bf16_f32 v180, v164, v165
	v_cvt_pk_bf16_f32 v181, v166, v167
	v_add_f32_e32 v177, v177, v178
	v_add_f32_e32 v179, v179, v177
	global_store_dwordx2 v175, v[180:181], s[48:49] offset:256 nt
	s_waitcnt vmcnt(32)
	v_pk_add_f32 v[170:171], v[84:85], v[170:171]
	v_pk_add_f32 v[168:169], v[82:83], v[168:169]
	global_store_dwordx4 v174, v[168:171], s[12:13] offset:576 nt
	v_mul_f32_e32 v178, v171, v171
	v_mul_f32_e32 v177, v169, v169
	v_fmac_f32_e32 v177, v168, v168
	v_fmac_f32_e32 v178, v170, v170
	v_cvt_pk_bf16_f32 v182, v168, v169
	v_cvt_pk_bf16_f32 v183, v170, v171
	v_add_f32_e32 v177, v177, v178
	v_add_f32_e32 v179, v179, v177
	global_store_dwordx2 v175, v[182:183], s[48:49] offset:288 nt
	ds_bpermute_b32 v177, v141, v179
	s_waitcnt lgkmcnt(0)
	v_add_f32_e32 v179, v179, v177
	ds_bpermute_b32 v178, v172, v179
	s_waitcnt lgkmcnt(0)
	v_add_f32_e32 v179, v179, v178
	s_and_saveexec_b64 s[62:63], s[4:5]
	global_store_dword v176, v179, s[14:15]
	s_mov_b64 exec, s[62:63]
	v_add_u32_e32 v173, 0x90000, v138
	global_load_dwordx4 v[156:159], v173, s[18:19]
	global_load_dwordx4 v[160:163], v173, s[18:19] offset:64
	global_load_dwordx4 v[164:167], v173, s[18:19] offset:512
	global_load_dwordx4 v[168:171], v173, s[18:19] offset:576
	v_add_u32_e32 v174, 0x30000, v138
	v_add_u32_e32 v175, 0x18000, v139
	v_add_u32_e32 v176, 0xc00, v140
	s_waitcnt vmcnt(29)
	v_pk_add_f32 v[200:201], v[80:81], v[200:201]
	v_pk_add_f32 v[198:199], v[78:79], v[198:199]
	global_store_dwordx4 v174, v[198:201], s[12:13] nt
	v_mul_f32_e32 v178, v201, v201
	v_mul_f32_e32 v177, v199, v199
	v_fmac_f32_e32 v177, v198, v198
	v_fmac_f32_e32 v178, v200, v200
	v_cvt_pk_bf16_f32 v180, v198, v199
	v_cvt_pk_bf16_f32 v181, v200, v201
	v_add_f32_e32 v179, v177, v178
	global_store_dwordx2 v175, v[180:181], s[48:49] nt
	s_waitcnt vmcnt(30)
	v_pk_add_f32 v[204:205], v[76:77], v[204:205]
	v_pk_add_f32 v[202:203], v[74:75], v[202:203]
	global_store_dwordx4 v174, v[202:205], s[12:13] offset:64 nt
	v_mul_f32_e32 v178, v205, v205
	v_mul_f32_e32 v177, v203, v203
	v_fmac_f32_e32 v177, v202, v202
	v_fmac_f32_e32 v178, v204, v204
	v_cvt_pk_bf16_f32 v182, v202, v203
	v_cvt_pk_bf16_f32 v183, v204, v205
	v_add_f32_e32 v177, v177, v178
	v_add_f32_e32 v179, v179, v177
	global_store_dwordx2 v175, v[182:183], s[48:49] offset:32 nt
	s_waitcnt vmcnt(31)
	v_pk_add_f32 v[208:209], v[72:73], v[208:209]
	v_pk_add_f32 v[206:207], v[70:71], v[206:207]
	global_store_dwordx4 v174, v[206:209], s[12:13] offset:512 nt
	v_mul_f32_e32 v178, v209, v209
	v_mul_f32_e32 v177, v207, v207
	v_fmac_f32_e32 v177, v206, v206
	v_fmac_f32_e32 v178, v208, v208
	v_cvt_pk_bf16_f32 v180, v206, v207
	v_cvt_pk_bf16_f32 v181, v208, v209
	v_add_f32_e32 v177, v177, v178
	v_add_f32_e32 v179, v179, v177
	global_store_dwordx2 v175, v[180:181], s[48:49] offset:256 nt
	s_waitcnt vmcnt(32)
	v_pk_add_f32 v[212:213], v[68:69], v[212:213]
	v_pk_add_f32 v[210:211], v[66:67], v[210:211]
	global_store_dwordx4 v174, v[210:213], s[12:13] offset:576 nt
	v_mul_f32_e32 v178, v213, v213
	v_mul_f32_e32 v177, v211, v211
	v_fmac_f32_e32 v177, v210, v210
	v_fmac_f32_e32 v178, v212, v212
	v_cvt_pk_bf16_f32 v182, v210, v211
	v_cvt_pk_bf16_f32 v183, v212, v213
	v_add_f32_e32 v177, v177, v178
	v_add_f32_e32 v179, v179, v177
	global_store_dwordx2 v175, v[182:183], s[48:49] offset:288 nt
	ds_bpermute_b32 v177, v141, v179
	s_waitcnt lgkmcnt(0)
	v_add_f32_e32 v179, v179, v177
	ds_bpermute_b32 v178, v172, v179
	s_waitcnt lgkmcnt(0)
	v_add_f32_e32 v179, v179, v178
	s_and_saveexec_b64 s[62:63], s[4:5]
	global_store_dword v176, v179, s[14:15]
	s_mov_b64 exec, s[62:63]
	v_add_u32_e32 v173, 0xa0000, v138
	global_load_dwordx4 v[198:201], v173, s[18:19]
	global_load_dwordx4 v[202:205], v173, s[18:19] offset:64
	global_load_dwordx4 v[206:209], v173, s[18:19] offset:512
	global_load_dwordx4 v[210:213], v173, s[18:19] offset:576
	v_add_u32_e32 v174, 0x80000, v138
	v_add_u32_e32 v175, 0x40000, v139
	v_add_u32_e32 v176, 0x2000, v140
	s_waitcnt vmcnt(29)
; __device__ __forceinline__ unsigned cvt_pk_bf16(float lo, float hi) { unsigned r; asm volatile("v_cvt_pk_bf16_f32 %0, %1, %2" : "=v"(r) : "v"(lo), "v"(hi)); return r; }
;     __device__ __forceinline__ void operator()(const f32x4 (&acc)[2][2][4][2], const pg8::Unit& u, int wr, int wc, int fr, int fq, LAS unsigned char*) const {
;     ...
;                 const int row = row0 + ai * 128 + m * 16; const size_t off = (size_t)row * DM + col0; float q = 0.f;
; #pragma unroll
;                 for (int bj = 0; bj < 2; ++bj)
; #pragma unroll
;                     for (int n = 0; n < 2; ++n) { const size_t o = off + bj * 128 + n * 16; const f32x4 xv = *(const f32x4*)(xin + o) + acc[ai][bj][m][n]; *(f32x4*)(xout + o) = xv;
;                         q += (xv[0] * xv[0] + xv[1] * xv[1]) + (xv[2] * xv[2] + xv[3] * xv[3]);
;                         u32x2 w; w.x = cvt_pk_bf16(xv[0], xv[1]); w.y = cvt_pk_bf16(xv[2], xv[3]); *(u32x2*)(xb + o) = w; }
;                 q += __shfl_xor(q, 16); q += __shfl_xor(q, 32);
;                 if (fq == 0) ssq[(size_t)row * 16 + u.pn * 4 + wc] = q;
	v_pk_add_f32 v[216:217], v[64:65], v[216:217]
	v_pk_add_f32 v[214:215], v[62:63], v[214:215]
	global_store_dwordx4 v174, v[214:217], s[12:13] nt
	v_mul_f32_e32 v178, v217, v217
	v_mul_f32_e32 v177, v215, v215
	v_fmac_f32_e32 v177, v214, v214
	v_fmac_f32_e32 v178, v216, v216
	v_cvt_pk_bf16_f32 v180, v214, v215
	v_cvt_pk_bf16_f32 v181, v216, v217
	v_add_f32_e32 v179, v177, v178
	global_store_dwordx2 v175, v[180:181], s[48:49] nt
	s_waitcnt vmcnt(30)
	v_pk_add_f32 v[220:221], v[60:61], v[220:221]
	v_pk_add_f32 v[218:219], v[58:59], v[218:219]
	global_store_dwordx4 v174, v[218:221], s[12:13] offset:64 nt
	v_mul_f32_e32 v178, v221, v221
	v_mul_f32_e32 v177, v219, v219
	v_fmac_f32_e32 v177, v218, v218
	v_fmac_f32_e32 v178, v220, v220
	v_cvt_pk_bf16_f32 v182, v218, v219
	v_cvt_pk_bf16_f32 v183, v220, v221
	v_add_f32_e32 v177, v177, v178
	v_add_f32_e32 v179, v179, v177
	global_store_dwordx2 v175, v[182:183], s[48:49] offset:32 nt
	s_waitcnt vmcnt(31)
	v_pk_add_f32 v[224:225], v[56:57], v[224:225]
	v_pk_add_f32 v[222:223], v[54:55], v[222:223]
	global_store_dwordx4 v174, v[222:225], s[12:13] offset:512 nt
	v_mul_f32_e32 v178, v225, v225
	v_mul_f32_e32 v177, v223, v223
	v_fmac_f32_e32 v177, v222, v222
	v_fmac_f32_e32 v178, v224, v224
	v_cvt_pk_bf16_f32 v180, v222, v223
	v_cvt_pk_bf16_f32 v181, v224, v225
	v_add_f32_e32 v177, v177, v178
	v_add_f32_e32 v179, v179, v177
	global_store_dwordx2 v175, v[180:181], s[48:49] offset:256 nt
	s_waitcnt vmcnt(32)
	v_pk_add_f32 v[228:229], v[52:53], v[228:229]
	v_pk_add_f32 v[226:227], v[50:51], v[226:227]
	global_store_dwordx4 v174, v[226:229], s[12:13] offset:576 nt
	v_mul_f32_e32 v178, v229, v229
	v_mul_f32_e32 v177, v227, v227
	v_fmac_f32_e32 v177, v226, v226
	v_fmac_f32_e32 v178, v228, v228
	v_cvt_pk_bf16_f32 v182, v226, v227
	v_cvt_pk_bf16_f32 v183, v228, v229
	v_add_f32_e32 v177, v177, v178
	v_add_f32_e32 v179, v179, v177
	global_store_dwordx2 v175, v[182:183], s[48:49] offset:288 nt
	ds_bpermute_b32 v177, v141, v179
	s_waitcnt lgkmcnt(0)
	v_add_f32_e32 v179, v179, v177
	ds_bpermute_b32 v178, v172, v179
	s_waitcnt lgkmcnt(0)
	v_add_f32_e32 v179, v179, v178
	s_and_saveexec_b64 s[62:63], s[4:5]
	global_store_dword v176, v179, s[14:15]
	s_mov_b64 exec, s[62:63]
	v_add_u32_e32 v173, 0xb0000, v138
	global_load_dwordx4 v[214:217], v173, s[18:19]
	global_load_dwordx4 v[218:221], v173, s[18:19] offset:64
	global_load_dwordx4 v[222:225], v173, s[18:19] offset:512
	global_load_dwordx4 v[226:229], v173, s[18:19] offset:576
	v_add_u32_e32 v174, 0x90000, v138
	v_add_u32_e32 v175, 0x48000, v139
	v_add_u32_e32 v176, 0x2400, v140
	s_waitcnt vmcnt(29)
	v_pk_add_f32 v[158:159], v[48:49], v[158:159]
	v_pk_add_f32 v[156:157], v[46:47], v[156:157]
	global_store_dwordx4 v174, v[156:159], s[12:13] nt
	v_mul_f32_e32 v178, v159, v159
	v_mul_f32_e32 v177, v157, v157
	v_fmac_f32_e32 v177, v156, v156
	v_fmac_f32_e32 v178, v158, v158
	v_cvt_pk_bf16_f32 v180, v156, v157
	v_cvt_pk_bf16_f32 v181, v158, v159
	v_add_f32_e32 v179, v177, v178
	global_store_dwordx2 v175, v[180:181], s[48:49] nt
	s_waitcnt vmcnt(30)
	v_pk_add_f32 v[162:163], v[44:45], v[162:163]
	v_pk_add_f32 v[160:161], v[42:43], v[160:161]
	global_store_dwordx4 v174, v[160:163], s[12:13] offset:64 nt
	v_mul_f32_e32 v178, v163, v163
	v_mul_f32_e32 v177, v161, v161
	v_fmac_f32_e32 v177, v160, v160
	v_fmac_f32_e32 v178, v162, v162
	v_cvt_pk_bf16_f32 v182, v160, v161
	v_cvt_pk_bf16_f32 v183, v162, v163
	v_add_f32_e32 v177, v177, v178
	v_add_f32_e32 v179, v179, v177
	global_store_dwordx2 v175, v[182:183], s[48:49] offset:32 nt
	s_waitcnt vmcnt(31)
	v_pk_add_f32 v[166:167], v[40:41], v[166:167]
	v_pk_add_f32 v[164:165], v[38:39], v[164:165]
	global_store_dwordx4 v174, v[164:167], s[12:13] offset:512 nt
	v_mul_f32_e32 v178, v167, v167
	v_mul_f32_e32 v177, v165, v165
	v_fmac_f32_e32 v177, v164, v164
	v_fmac_f32_e32 v178, v166, v166
	v_cvt_pk_bf16_f32 v180, v164, v165
	v_cvt_pk_bf16_f32 v181, v166, v167
	v_add_f32_e32 v177, v177, v178
	v_add_f32_e32 v179, v179, v177
	global_store_dwordx2 v175, v[180:181], s[48:49] offset:256 nt
	s_waitcnt vmcnt(32)
	v_pk_add_f32 v[170:171], v[36:37], v[170:171]
	v_pk_add_f32 v[168:169], v[34:35], v[168:169]
	global_store_dwordx4 v174, v[168:171], s[12:13] offset:576 nt
	v_mul_f32_e32 v178, v171, v171
	v_mul_f32_e32 v177, v169, v169
	v_fmac_f32_e32 v177, v168, v168
	v_fmac_f32_e32 v178, v170, v170
	v_cvt_pk_bf16_f32 v182, v168, v169
	v_cvt_pk_bf16_f32 v183, v170, v171
	v_add_f32_e32 v177, v177, v178
	v_add_f32_e32 v179, v179, v177
	global_store_dwordx2 v175, v[182:183], s[48:49] offset:288 nt
	ds_bpermute_b32 v177, v141, v179
	s_waitcnt lgkmcnt(0)
	v_add_f32_e32 v179, v179, v177
	ds_bpermute_b32 v178, v172, v179
	s_waitcnt lgkmcnt(0)
	v_add_f32_e32 v179, v179, v178
	s_and_saveexec_b64 s[62:63], s[4:5]
	global_store_dword v176, v179, s[14:15]
	s_mov_b64 exec, s[62:63]
	v_add_u32_e32 v174, 0xa0000, v138
	v_add_u32_e32 v175, 0x50000, v139
	v_add_u32_e32 v176, 0x2800, v140
	s_waitcnt vmcnt(25)
; __device__ __forceinline__ unsigned cvt_pk_bf16(float lo, float hi) { unsigned r; asm volatile("v_cvt_pk_bf16_f32 %0, %1, %2" : "=v"(r) : "v"(lo), "v"(hi)); return r; }
;     __device__ __forceinline__ void operator()(const f32x4 (&acc)[2][2][4][2], const pg8::Unit& u, int wr, int wc, int fr, int fq, LAS unsigned char*) const {
;     ...
;                 const int row = row0 + ai * 128 + m * 16; const size_t off = (size_t)row * DM + col0; float q = 0.f;
; #pragma unroll
;                 for (int bj = 0; bj < 2; ++bj)
; #pragma unroll
;                     for (int n = 0; n < 2; ++n) { const size_t o = off + bj * 128 + n * 16; const f32x4 xv = *(const f32x4*)(xin + o) + acc[ai][bj][m][n]; *(f32x4*)(xout + o) = xv;
;                         q += (xv[0] * xv[0] + xv[1] * xv[1]) + (xv[2] * xv[2] + xv[3] * xv[3]);
;                         u32x2 w; w.x = cvt_pk_bf16(xv[0], xv[1]); w.y = cvt_pk_bf16(xv[2], xv[3]); *(u32x2*)(xb + o) = w; }
;                 q += __shfl_xor(q, 16); q += __shfl_xor(q, 32);
;                 if (fq == 0) ssq[(size_t)row * 16 + u.pn * 4 + wc] = q;
	v_pk_add_f32 v[200:201], v[32:33], v[200:201]
	v_pk_add_f32 v[198:199], v[30:31], v[198:199]
	global_store_dwordx4 v174, v[198:201], s[12:13] nt
	v_mul_f32_e32 v178, v201, v201
	v_mul_f32_e32 v177, v199, v199
	v_fmac_f32_e32 v177, v198, v198
	v_fmac_f32_e32 v178, v200, v200
	v_cvt_pk_bf16_f32 v180, v198, v199
	v_cvt_pk_bf16_f32 v181, v200, v201
	v_add_f32_e32 v179, v177, v178
	global_store_dwordx2 v175, v[180:181], s[48:49] nt
	s_waitcnt vmcnt(26)
	v_pk_add_f32 v[204:205], v[28:29], v[204:205]
	v_pk_add_f32 v[202:203], v[26:27], v[202:203]
	global_store_dwordx4 v174, v[202:205], s[12:13] offset:64 nt
	v_mul_f32_e32 v178, v205, v205
	v_mul_f32_e32 v177, v203, v203
	v_fmac_f32_e32 v177, v202, v202
	v_fmac_f32_e32 v178, v204, v204
	v_cvt_pk_bf16_f32 v182, v202, v203
	v_cvt_pk_bf16_f32 v183, v204, v205
	v_add_f32_e32 v177, v177, v178
	v_add_f32_e32 v179, v179, v177
	global_store_dwordx2 v175, v[182:183], s[48:49] offset:32 nt
	s_waitcnt vmcnt(27)
	v_pk_add_f32 v[208:209], v[24:25], v[208:209]
	v_pk_add_f32 v[206:207], v[22:23], v[206:207]
	global_store_dwordx4 v174, v[206:209], s[12:13] offset:512 nt
	v_mul_f32_e32 v178, v209, v209
	v_mul_f32_e32 v177, v207, v207
	v_fmac_f32_e32 v177, v206, v206
	v_fmac_f32_e32 v178, v208, v208
	v_cvt_pk_bf16_f32 v180, v206, v207
	v_cvt_pk_bf16_f32 v181, v208, v209
	v_add_f32_e32 v177, v177, v178
	v_add_f32_e32 v179, v179, v177
	global_store_dwordx2 v175, v[180:181], s[48:49] offset:256 nt
	s_waitcnt vmcnt(28)
	v_pk_add_f32 v[212:213], v[20:21], v[212:213]
	v_pk_add_f32 v[210:211], v[18:19], v[210:211]
	global_store_dwordx4 v174, v[210:213], s[12:13] offset:576 nt
	v_mul_f32_e32 v178, v213, v213
	v_mul_f32_e32 v177, v211, v211
	v_fmac_f32_e32 v177, v210, v210
	v_fmac_f32_e32 v178, v212, v212
	v_cvt_pk_bf16_f32 v182, v210, v211
	v_cvt_pk_bf16_f32 v183, v212, v213
	v_add_f32_e32 v177, v177, v178
	v_add_f32_e32 v179, v179, v177
	global_store_dwordx2 v175, v[182:183], s[48:49] offset:288 nt
	ds_bpermute_b32 v177, v141, v179
	s_waitcnt lgkmcnt(0)
	v_add_f32_e32 v179, v179, v177
	ds_bpermute_b32 v178, v172, v179
	s_waitcnt lgkmcnt(0)
	v_add_f32_e32 v179, v179, v178
	s_and_saveexec_b64 s[62:63], s[4:5]
	global_store_dword v176, v179, s[14:15]
	s_mov_b64 exec, s[62:63]
	v_add_u32_e32 v174, 0xb0000, v138
	v_add_u32_e32 v175, 0x58000, v139
	v_add_u32_e32 v176, 0x2c00, v140
	s_waitcnt vmcnt(21)
	v_pk_add_f32 v[216:217], v[16:17], v[216:217]
	v_pk_add_f32 v[214:215], v[14:15], v[214:215]
	global_store_dwordx4 v174, v[214:217], s[12:13] nt
	v_mul_f32_e32 v178, v217, v217
	v_mul_f32_e32 v177, v215, v215
	v_fmac_f32_e32 v177, v214, v214
	v_fmac_f32_e32 v178, v216, v216
	v_cvt_pk_bf16_f32 v180, v214, v215
	v_cvt_pk_bf16_f32 v181, v216, v217
	v_add_f32_e32 v179, v177, v178
	global_store_dwordx2 v175, v[180:181], s[48:49] nt
	s_waitcnt vmcnt(22)
	v_pk_add_f32 v[220:221], v[12:13], v[220:221]
	v_pk_add_f32 v[218:219], v[10:11], v[218:219]
	global_store_dwordx4 v174, v[218:221], s[12:13] offset:64 nt
	v_mul_f32_e32 v178, v221, v221
	v_mul_f32_e32 v177, v219, v219
	v_fmac_f32_e32 v177, v218, v218
	v_fmac_f32_e32 v178, v220, v220
	v_cvt_pk_bf16_f32 v182, v218, v219
	v_cvt_pk_bf16_f32 v183, v220, v221
	v_add_f32_e32 v177, v177, v178
	v_add_f32_e32 v179, v179, v177
	global_store_dwordx2 v175, v[182:183], s[48:49] offset:32 nt
	s_waitcnt vmcnt(23)
	v_pk_add_f32 v[224:225], v[8:9], v[224:225]
	v_pk_add_f32 v[222:223], v[6:7], v[222:223]
	global_store_dwordx4 v174, v[222:225], s[12:13] offset:512 nt
	v_mul_f32_e32 v178, v225, v225
	v_mul_f32_e32 v177, v223, v223
	v_fmac_f32_e32 v177, v222, v222
	v_fmac_f32_e32 v178, v224, v224
	v_cvt_pk_bf16_f32 v180, v222, v223
	v_cvt_pk_bf16_f32 v181, v224, v225
	v_add_f32_e32 v177, v177, v178
	v_add_f32_e32 v179, v179, v177
	global_store_dwordx2 v175, v[180:181], s[48:49] offset:256 nt
	s_waitcnt vmcnt(24)
	v_pk_add_f32 v[228:229], v[4:5], v[228:229]
	v_pk_add_f32 v[226:227], v[2:3], v[226:227]
	global_store_dwordx4 v174, v[226:229], s[12:13] offset:576 nt
	v_mul_f32_e32 v178, v229, v229
	v_mul_f32_e32 v177, v227, v227
	v_fmac_f32_e32 v177, v226, v226
	v_fmac_f32_e32 v178, v228, v228
	v_cvt_pk_bf16_f32 v182, v226, v227
	v_cvt_pk_bf16_f32 v183, v228, v229
	v_add_f32_e32 v177, v177, v178
	v_add_f32_e32 v179, v179, v177
	global_store_dwordx2 v175, v[182:183], s[48:49] offset:288 nt
	ds_bpermute_b32 v177, v141, v179
	s_waitcnt lgkmcnt(0)
	v_add_f32_e32 v179, v179, v177
	ds_bpermute_b32 v178, v172, v179
	s_waitcnt lgkmcnt(0)
	v_add_f32_e32 v179, v179, v178
	s_and_saveexec_b64 s[62:63], s[4:5]
	global_store_dword v176, v179, s[14:15]
	s_mov_b64 exec, s[62:63]
	s_andn2_b64 vcc, exec, s[6:7]
	s_mov_b64 s[6:7], -1
	s_cbranch_vccnz .LBB0_53
	s_andn2_b64 vcc, exec, s[22:23]
	s_cbranch_vccnz .LBB0_52
	s_barrier
	s_branch .LBB0_52

; __device__ __forceinline__ unsigned cvt_pk_bf16(float lo, float hi) { unsigned r; asm volatile("v_cvt_pk_bf16_f32 %0, %1, %2" : "=v"(r) : "v"(lo), "v"(hi)); return r; }
; __device__ __forceinline__ float bflo(unsigned w) { return __uint_as_float(w << 16); }
; __device__ __forceinline__ float bfhi(unsigned w) { return __uint_as_float(w & 0xffff0000u); }
;     __device__ __forceinline__ void operator()(f32x4 (&acc)[2][2][4][2], const pg8::Unit& u, int wr, int wc, int fr, int fq, LAS unsigned char*) const {
;     ...
;                 const int row = row0 + ai * 128 + m * 16;
; #pragma unroll
;                 for (int bj = 0; bj < 2; ++bj) {
;                     const int col = col0 + bj * 128;
;                     const u32x4 gw = *(const u32x4*)(gates + (size_t)row * 3072 + 2048 + col);
;                     const f32x4 v0 = acc[ai][bj][m][0], v1 = acc[ai][bj][m][1];
;                     u32x4 w; w.x = cvt_pk_bf16(v0[0] * bflo(gw.x), v0[1] * bfhi(gw.x)); w.y = cvt_pk_bf16(v0[2] * bflo(gw.y), v0[3] * bfhi(gw.y));
;                     w.z = cvt_pk_bf16(v1[0] * bflo(gw.z), v1[1] * bfhi(gw.z)); w.w = cvt_pk_bf16(v1[2] * bflo(gw.w), v1[3] * bfhi(gw.w));
;                     *(u32x4*)(Y + (size_t)row * DM + col) = w;
.LBB0_114:
	v_add_u32_e32 v134, s23, v166
	v_or_b32_e32 v132, s84, v168
	v_mov_b64_e32 v[136:137], s[12:13]
	v_mad_i64_i32 v[130:131], s[26:27], v134, s82, v[136:137]
	v_ashrrev_i32_e32 v133, 31, v132
	v_lshl_add_u64 v[162:163], v[130:131], 0, s[38:39]
	v_lshlrev_b64 v[130:131], 1, v[132:133]
	v_lshl_add_u64 v[158:159], v[162:163], 0, v[130:131]
	global_load_dwordx4 v[158:161], v[158:159], off
	v_or_b32_e32 v132, 0x80, v132
	v_ashrrev_i32_e32 v133, 31, v132
	v_lshlrev_b64 v[132:133], 1, v[132:133]
	v_lshl_add_u64 v[162:163], v[162:163], 0, v[132:133]
	s_andn2_b64 vcc, exec, s[4:5]
	s_mov_b64 s[4:5], -1
	s_waitcnt vmcnt(0)
	v_lshlrev_b32_e32 v135, 16, v158
	v_and_b32_e32 v158, 0xffff0000, v158
	v_lshlrev_b32_e32 v170, 16, v159
	v_and_b32_e32 v159, 0xffff0000, v159
	v_lshlrev_b32_e32 v172, 16, v161
	v_and_b32_e32 v161, 0xffff0000, v161
	v_lshlrev_b32_e32 v171, 16, v160
	v_and_b32_e32 v160, 0xffff0000, v160
	v_mul_f32_e32 v126, v126, v135
	v_mul_f32_e32 v127, v127, v158
	v_mul_f32_e32 v128, v128, v170
	v_mul_f32_e32 v129, v129, v159
	v_mul_f32_e32 v125, v125, v161
	v_mul_f32_e32 v135, v122, v171
	v_mul_f32_e32 v158, v123, v160
	v_mul_f32_e32 v159, v124, v172
	v_cvt_pk_bf16_f32 v122, v126, v127
	v_cvt_pk_bf16_f32 v123, v128, v129
	v_cvt_pk_bf16_f32 v124, v135, v158
	v_cvt_pk_bf16_f32 v125, v159, v125
	global_load_dwordx4 v[126:129], v[162:163], off
	v_ashrrev_i32_e32 v135, 31, v134
	v_lshlrev_b64 v[160:161], 11, v[134:135]
	v_or_b32_e32 v158, 16, v134
	v_lshl_add_u64 v[160:161], s[14:15], 0, v[160:161]
	v_mad_i64_i32 v[162:163], s[26:27], v158, s82, v[136:137]
	v_lshl_add_u64 v[160:161], v[160:161], 0, v[130:131]
	v_lshl_add_u64 v[162:163], v[162:163], 0, s[38:39]
	global_store_dwordx4 v[160:161], v[122:125], off nt
	v_lshl_add_u64 v[170:171], v[162:163], 0, v[130:131]
	v_ashrrev_i32_e32 v159, 31, v158
	s_waitcnt vmcnt(1)
	v_lshlrev_b32_e32 v122, 16, v126
	v_and_b32_e32 v123, 0xffff0000, v126
	v_lshlrev_b32_e32 v124, 16, v127
	v_and_b32_e32 v125, 0xffff0000, v127
	v_lshlrev_b32_e32 v126, 16, v128
	v_and_b32_e32 v127, 0xffff0000, v128
	v_lshlrev_b32_e32 v128, 16, v129
	v_and_b32_e32 v129, 0xffff0000, v129
	v_mul_f32_e32 v118, v118, v122
	v_mul_f32_e32 v119, v119, v123
	v_mul_f32_e32 v120, v120, v124
	v_mul_f32_e32 v121, v121, v125
	v_mul_f32_e32 v117, v117, v129
	v_mul_f32_e32 v122, v114, v126
	v_mul_f32_e32 v123, v115, v127
	v_mul_f32_e32 v124, v116, v128
	v_cvt_pk_bf16_f32 v114, v118, v119
	v_cvt_pk_bf16_f32 v115, v120, v121
	v_cvt_pk_bf16_f32 v116, v122, v123
	v_cvt_pk_bf16_f32 v117, v124, v117
	global_load_dwordx4 v[118:121], v[170:171], off
	v_lshl_add_u64 v[122:123], v[162:163], 0, v[132:133]
	global_store_dwordx4 v[160:161], v[114:117], off offset:256 nt
	s_waitcnt vmcnt(1)
	s_nop 0
	v_lshlrev_b32_e32 v114, 16, v118
	v_and_b32_e32 v115, 0xffff0000, v118
	v_lshlrev_b32_e32 v116, 16, v119
	v_and_b32_e32 v117, 0xffff0000, v119
	v_lshlrev_b32_e32 v118, 16, v120
	v_and_b32_e32 v119, 0xffff0000, v120
	v_lshlrev_b32_e32 v120, 16, v121
	v_and_b32_e32 v121, 0xffff0000, v121
	v_mul_f32_e32 v110, v110, v114
	v_mul_f32_e32 v111, v111, v115
	v_mul_f32_e32 v112, v112, v116
	v_mul_f32_e32 v113, v113, v117
	v_mul_f32_e32 v109, v109, v121
	v_mul_f32_e32 v114, v106, v118
	v_mul_f32_e32 v115, v107, v119
	v_mul_f32_e32 v116, v108, v120
	v_cvt_pk_bf16_f32 v106, v110, v111
	v_cvt_pk_bf16_f32 v107, v112, v113
	v_cvt_pk_bf16_f32 v108, v114, v115
	v_cvt_pk_bf16_f32 v109, v116, v109
	global_load_dwordx4 v[110:113], v[122:123], off
	v_lshlrev_b64 v[118:119], 11, v[158:159]
	v_or_b32_e32 v114, 32, v134
	v_lshl_add_u64 v[118:119], s[14:15], 0, v[118:119]
	v_mad_i64_i32 v[116:117], s[26:27], v114, s82, v[136:137]
	v_lshl_add_u64 v[118:119], v[118:119], 0, v[130:131]
	v_lshl_add_u64 v[116:117], v[116:117], 0, s[38:39]
	global_store_dwordx4 v[118:119], v[106:109], off nt
	v_lshl_add_u64 v[120:121], v[116:117], 0, v[130:131]
	v_ashrrev_i32_e32 v115, 31, v114
	s_waitcnt vmcnt(1)
	v_lshlrev_b32_e32 v106, 16, v110
	v_and_b32_e32 v107, 0xffff0000, v110
	v_lshlrev_b32_e32 v108, 16, v111
	v_and_b32_e32 v109, 0xffff0000, v111
	v_lshlrev_b32_e32 v110, 16, v112
	v_and_b32_e32 v111, 0xffff0000, v112
	v_lshlrev_b32_e32 v112, 16, v113
	v_and_b32_e32 v113, 0xffff0000, v113
	v_mul_f32_e32 v102, v102, v106
	v_mul_f32_e32 v103, v103, v107
	v_mul_f32_e32 v104, v104, v108
	v_mul_f32_e32 v105, v105, v109
	v_mul_f32_e32 v101, v101, v113
	v_mul_f32_e32 v106, v98, v110
	v_mul_f32_e32 v107, v99, v111
	v_mul_f32_e32 v108, v100, v112
	v_cvt_pk_bf16_f32 v98, v102, v103
	v_cvt_pk_bf16_f32 v99, v104, v105
	v_cvt_pk_bf16_f32 v100, v106, v107
	v_cvt_pk_bf16_f32 v101, v108, v101
	global_load_dwordx4 v[102:105], v[120:121], off
	v_lshl_add_u64 v[106:107], v[116:117], 0, v[132:133]
	global_store_dwordx4 v[118:119], v[98:101], off offset:256 nt
	s_waitcnt vmcnt(1)
	s_nop 0
	v_lshlrev_b32_e32 v98, 16, v102
	v_and_b32_e32 v99, 0xffff0000, v102
	v_lshlrev_b32_e32 v100, 16, v103
	v_and_b32_e32 v101, 0xffff0000, v103
	v_lshlrev_b32_e32 v102, 16, v104
	v_and_b32_e32 v103, 0xffff0000, v104
	v_lshlrev_b32_e32 v104, 16, v105
	v_and_b32_e32 v105, 0xffff0000, v105
	v_mul_f32_e32 v94, v94, v98
	v_mul_f32_e32 v95, v95, v99
	v_mul_f32_e32 v96, v96, v100
	v_mul_f32_e32 v97, v97, v101
	v_mul_f32_e32 v93, v93, v105
	v_mul_f32_e32 v98, v90, v102
	v_mul_f32_e32 v99, v91, v103
	v_mul_f32_e32 v100, v92, v104
	v_cvt_pk_bf16_f32 v90, v94, v95
	v_cvt_pk_bf16_f32 v91, v96, v97
	v_cvt_pk_bf16_f32 v92, v98, v99
	v_cvt_pk_bf16_f32 v93, v100, v93
	global_load_dwordx4 v[94:97], v[106:107], off
	v_lshlrev_b64 v[102:103], 11, v[114:115]
	v_or_b32_e32 v98, 48, v134
	v_lshl_add_u64 v[102:103], s[14:15], 0, v[102:103]
	v_mad_i64_i32 v[100:101], s[26:27], v98, s82, v[136:137]
	v_lshl_add_u64 v[102:103], v[102:103], 0, v[130:131]
	v_lshl_add_u64 v[100:101], v[100:101], 0, s[38:39]
	global_store_dwordx4 v[102:103], v[90:93], off nt
	v_lshl_add_u64 v[104:105], v[100:101], 0, v[130:131]
	v_ashrrev_i32_e32 v99, 31, v98
	s_waitcnt vmcnt(1)
; __device__ __forceinline__ unsigned cvt_pk_bf16(float lo, float hi) { unsigned r; asm volatile("v_cvt_pk_bf16_f32 %0, %1, %2" : "=v"(r) : "v"(lo), "v"(hi)); return r; }
; __device__ __forceinline__ float bflo(unsigned w) { return __uint_as_float(w << 16); }
; __device__ __forceinline__ float bfhi(unsigned w) { return __uint_as_float(w & 0xffff0000u); }
;     __device__ __forceinline__ void operator()(f32x4 (&acc)[2][2][4][2], const pg8::Unit& u, int wr, int wc, int fr, int fq, LAS unsigned char*) const {
;     ...
;                 const int row = row0 + ai * 128 + m * 16;
; #pragma unroll
;                 for (int bj = 0; bj < 2; ++bj) {
;                     const int col = col0 + bj * 128;
;                     const u32x4 gw = *(const u32x4*)(gates + (size_t)row * 3072 + 2048 + col);
;                     const f32x4 v0 = acc[ai][bj][m][0], v1 = acc[ai][bj][m][1];
;                     u32x4 w; w.x = cvt_pk_bf16(v0[0] * bflo(gw.x), v0[1] * bfhi(gw.x)); w.y = cvt_pk_bf16(v0[2] * bflo(gw.y), v0[3] * bfhi(gw.y));
;                     w.z = cvt_pk_bf16(v1[0] * bflo(gw.z), v1[1] * bfhi(gw.z)); w.w = cvt_pk_bf16(v1[2] * bflo(gw.w), v1[3] * bfhi(gw.w));
;                     *(u32x4*)(Y + (size_t)row * DM + col) = w;
	v_lshlrev_b32_e32 v90, 16, v94
	v_and_b32_e32 v91, 0xffff0000, v94
	v_lshlrev_b32_e32 v92, 16, v95
	v_and_b32_e32 v93, 0xffff0000, v95
	v_lshlrev_b32_e32 v94, 16, v96
	v_and_b32_e32 v95, 0xffff0000, v96
	v_lshlrev_b32_e32 v96, 16, v97
	v_and_b32_e32 v97, 0xffff0000, v97
	v_mul_f32_e32 v86, v86, v90
	v_mul_f32_e32 v87, v87, v91
	v_mul_f32_e32 v88, v88, v92
	v_mul_f32_e32 v89, v89, v93
	v_mul_f32_e32 v85, v85, v97
	v_mul_f32_e32 v90, v82, v94
	v_mul_f32_e32 v91, v83, v95
	v_mul_f32_e32 v92, v84, v96
	v_cvt_pk_bf16_f32 v82, v86, v87
	v_cvt_pk_bf16_f32 v83, v88, v89
	v_cvt_pk_bf16_f32 v84, v90, v91
	v_cvt_pk_bf16_f32 v85, v92, v85
	global_load_dwordx4 v[86:89], v[104:105], off
	v_lshl_add_u64 v[90:91], v[100:101], 0, v[132:133]
	global_store_dwordx4 v[102:103], v[82:85], off offset:256 nt
	s_waitcnt vmcnt(1)
	s_nop 0
	v_lshlrev_b32_e32 v82, 16, v86
	v_and_b32_e32 v83, 0xffff0000, v86
	v_lshlrev_b32_e32 v84, 16, v87
	v_and_b32_e32 v85, 0xffff0000, v87
	v_lshlrev_b32_e32 v86, 16, v88
	v_and_b32_e32 v87, 0xffff0000, v88
	v_lshlrev_b32_e32 v88, 16, v89
	v_and_b32_e32 v89, 0xffff0000, v89
	v_mul_f32_e32 v78, v78, v82
	v_mul_f32_e32 v79, v79, v83
	v_mul_f32_e32 v80, v80, v84
	v_mul_f32_e32 v81, v81, v85
	v_mul_f32_e32 v77, v77, v89
	v_mul_f32_e32 v82, v74, v86
	v_mul_f32_e32 v83, v75, v87
	v_mul_f32_e32 v84, v76, v88
	v_cvt_pk_bf16_f32 v74, v78, v79
	v_cvt_pk_bf16_f32 v75, v80, v81
	v_cvt_pk_bf16_f32 v76, v82, v83
	v_cvt_pk_bf16_f32 v77, v84, v77
	global_load_dwordx4 v[78:81], v[90:91], off
	v_lshlrev_b64 v[86:87], 11, v[98:99]
	v_add_u32_e32 v82, 0x80, v134
	v_lshl_add_u64 v[86:87], s[14:15], 0, v[86:87]
	v_mad_i64_i32 v[84:85], s[26:27], v82, s82, v[136:137]
	v_lshl_add_u64 v[86:87], v[86:87], 0, v[130:131]
	v_lshl_add_u64 v[84:85], v[84:85], 0, s[38:39]
	global_store_dwordx4 v[86:87], v[74:77], off nt
	v_lshl_add_u64 v[88:89], v[84:85], 0, v[130:131]
	v_ashrrev_i32_e32 v83, 31, v82
	s_waitcnt vmcnt(1)
	v_lshlrev_b32_e32 v74, 16, v78
	v_and_b32_e32 v75, 0xffff0000, v78
	v_lshlrev_b32_e32 v76, 16, v79
	v_and_b32_e32 v77, 0xffff0000, v79
	v_lshlrev_b32_e32 v78, 16, v80
	v_and_b32_e32 v79, 0xffff0000, v80
	v_lshlrev_b32_e32 v80, 16, v81
	v_and_b32_e32 v81, 0xffff0000, v81
	v_mul_f32_e32 v70, v70, v74
	v_mul_f32_e32 v71, v71, v75
	v_mul_f32_e32 v72, v72, v76
	v_mul_f32_e32 v73, v73, v77
	v_mul_f32_e32 v69, v69, v81
	v_mul_f32_e32 v74, v66, v78
	v_mul_f32_e32 v75, v67, v79
	v_mul_f32_e32 v76, v68, v80
	v_cvt_pk_bf16_f32 v66, v70, v71
	v_cvt_pk_bf16_f32 v67, v72, v73
	v_cvt_pk_bf16_f32 v68, v74, v75
	v_cvt_pk_bf16_f32 v69, v76, v69
	global_load_dwordx4 v[70:73], v[88:89], off
	v_lshl_add_u64 v[74:75], v[84:85], 0, v[132:133]
	global_store_dwordx4 v[86:87], v[66:69], off offset:256 nt
	s_waitcnt vmcnt(1)
	s_nop 0
	v_lshlrev_b32_e32 v66, 16, v70
	v_and_b32_e32 v67, 0xffff0000, v70
	v_lshlrev_b32_e32 v68, 16, v71
	v_and_b32_e32 v69, 0xffff0000, v71
	v_lshlrev_b32_e32 v70, 16, v72
	v_and_b32_e32 v71, 0xffff0000, v72
	v_lshlrev_b32_e32 v72, 16, v73
	v_and_b32_e32 v73, 0xffff0000, v73
	v_mul_f32_e32 v62, v62, v66
	v_mul_f32_e32 v63, v63, v67
	v_mul_f32_e32 v64, v64, v68
	v_mul_f32_e32 v65, v65, v69
	v_mul_f32_e32 v61, v61, v73
	v_mul_f32_e32 v66, v58, v70
	v_mul_f32_e32 v67, v59, v71
	v_mul_f32_e32 v68, v60, v72
	v_cvt_pk_bf16_f32 v58, v62, v63
	v_cvt_pk_bf16_f32 v59, v64, v65
	v_cvt_pk_bf16_f32 v60, v66, v67
	v_cvt_pk_bf16_f32 v61, v68, v61
	global_load_dwordx4 v[62:65], v[74:75], off
	v_lshlrev_b64 v[70:71], 11, v[82:83]
	v_add_u32_e32 v66, 0x90, v134
	v_lshl_add_u64 v[70:71], s[14:15], 0, v[70:71]
	v_mad_i64_i32 v[68:69], s[26:27], v66, s82, v[136:137]
	v_lshl_add_u64 v[70:71], v[70:71], 0, v[130:131]
	v_lshl_add_u64 v[68:69], v[68:69], 0, s[38:39]
	global_store_dwordx4 v[70:71], v[58:61], off nt
	v_lshl_add_u64 v[72:73], v[68:69], 0, v[130:131]
	v_ashrrev_i32_e32 v67, 31, v66
	s_waitcnt vmcnt(1)
	v_lshlrev_b32_e32 v58, 16, v62
	v_and_b32_e32 v59, 0xffff0000, v62
	v_lshlrev_b32_e32 v60, 16, v63
	v_and_b32_e32 v61, 0xffff0000, v63
	v_lshlrev_b32_e32 v62, 16, v64
	v_and_b32_e32 v63, 0xffff0000, v64
	v_lshlrev_b32_e32 v64, 16, v65
	v_and_b32_e32 v65, 0xffff0000, v65
	v_mul_f32_e32 v54, v54, v58
	v_mul_f32_e32 v55, v55, v59
	v_mul_f32_e32 v56, v56, v60
	v_mul_f32_e32 v57, v57, v61
	v_mul_f32_e32 v53, v53, v65
	v_mul_f32_e32 v58, v50, v62
	v_mul_f32_e32 v59, v51, v63
	v_mul_f32_e32 v60, v52, v64
	v_cvt_pk_bf16_f32 v50, v54, v55
	v_cvt_pk_bf16_f32 v51, v56, v57
	v_cvt_pk_bf16_f32 v52, v58, v59
	v_cvt_pk_bf16_f32 v53, v60, v53
	global_load_dwordx4 v[54:57], v[72:73], off
	v_lshl_add_u64 v[58:59], v[68:69], 0, v[132:133]
	global_store_dwordx4 v[70:71], v[50:53], off offset:256 nt
	s_waitcnt vmcnt(1)
; __device__ __forceinline__ unsigned cvt_pk_bf16(float lo, float hi) { unsigned r; asm volatile("v_cvt_pk_bf16_f32 %0, %1, %2" : "=v"(r) : "v"(lo), "v"(hi)); return r; }
; __device__ __forceinline__ float bflo(unsigned w) { return __uint_as_float(w << 16); }
; __device__ __forceinline__ float bfhi(unsigned w) { return __uint_as_float(w & 0xffff0000u); }
;     __device__ __forceinline__ void operator()(f32x4 (&acc)[2][2][4][2], const pg8::Unit& u, int wr, int wc, int fr, int fq, LAS unsigned char*) const {
;     ...
;                 const int row = row0 + ai * 128 + m * 16;
; #pragma unroll
;                 for (int bj = 0; bj < 2; ++bj) {
;                     const int col = col0 + bj * 128;
;                     const u32x4 gw = *(const u32x4*)(gates + (size_t)row * 3072 + 2048 + col);
;                     const f32x4 v0 = acc[ai][bj][m][0], v1 = acc[ai][bj][m][1];
;                     u32x4 w; w.x = cvt_pk_bf16(v0[0] * bflo(gw.x), v0[1] * bfhi(gw.x)); w.y = cvt_pk_bf16(v0[2] * bflo(gw.y), v0[3] * bfhi(gw.y));
;                     w.z = cvt_pk_bf16(v1[0] * bflo(gw.z), v1[1] * bfhi(gw.z)); w.w = cvt_pk_bf16(v1[2] * bflo(gw.w), v1[3] * bfhi(gw.w));
;                     *(u32x4*)(Y + (size_t)row * DM + col) = w;
	s_nop 0
	v_lshlrev_b32_e32 v50, 16, v54
	v_and_b32_e32 v51, 0xffff0000, v54
	v_lshlrev_b32_e32 v52, 16, v55
	v_and_b32_e32 v53, 0xffff0000, v55
	v_lshlrev_b32_e32 v54, 16, v56
	v_and_b32_e32 v55, 0xffff0000, v56
	v_lshlrev_b32_e32 v56, 16, v57
	v_and_b32_e32 v57, 0xffff0000, v57
	v_mul_f32_e32 v46, v46, v50
	v_mul_f32_e32 v47, v47, v51
	v_mul_f32_e32 v48, v48, v52
	v_mul_f32_e32 v49, v49, v53
	v_mul_f32_e32 v45, v45, v57
	v_mul_f32_e32 v50, v42, v54
	v_mul_f32_e32 v51, v43, v55
	v_mul_f32_e32 v52, v44, v56
	v_cvt_pk_bf16_f32 v42, v46, v47
	v_cvt_pk_bf16_f32 v43, v48, v49
	v_cvt_pk_bf16_f32 v44, v50, v51
	v_cvt_pk_bf16_f32 v45, v52, v45
	global_load_dwordx4 v[46:49], v[58:59], off
	v_lshlrev_b64 v[54:55], 11, v[66:67]
	v_add_u32_e32 v50, 0xa0, v134
	v_lshl_add_u64 v[54:55], s[14:15], 0, v[54:55]
	v_mad_i64_i32 v[52:53], s[26:27], v50, s82, v[136:137]
	v_lshl_add_u64 v[54:55], v[54:55], 0, v[130:131]
	v_lshl_add_u64 v[52:53], v[52:53], 0, s[38:39]
	global_store_dwordx4 v[54:55], v[42:45], off nt
	v_lshl_add_u64 v[56:57], v[52:53], 0, v[130:131]
	v_ashrrev_i32_e32 v51, 31, v50
	s_waitcnt vmcnt(1)
	v_lshlrev_b32_e32 v42, 16, v46
	v_and_b32_e32 v43, 0xffff0000, v46
	v_lshlrev_b32_e32 v44, 16, v47
	v_and_b32_e32 v45, 0xffff0000, v47
	v_lshlrev_b32_e32 v46, 16, v48
	v_and_b32_e32 v47, 0xffff0000, v48
	v_lshlrev_b32_e32 v48, 16, v49
	v_and_b32_e32 v49, 0xffff0000, v49
	v_mul_f32_e32 v38, v38, v42
	v_mul_f32_e32 v39, v39, v43
	v_mul_f32_e32 v40, v40, v44
	v_mul_f32_e32 v41, v41, v45
	v_mul_f32_e32 v37, v37, v49
	v_mul_f32_e32 v42, v34, v46
	v_mul_f32_e32 v43, v35, v47
	v_mul_f32_e32 v44, v36, v48
	v_cvt_pk_bf16_f32 v34, v38, v39
	v_cvt_pk_bf16_f32 v35, v40, v41
	v_cvt_pk_bf16_f32 v36, v42, v43
	v_cvt_pk_bf16_f32 v37, v44, v37
	global_load_dwordx4 v[38:41], v[56:57], off
	v_lshl_add_u64 v[42:43], v[52:53], 0, v[132:133]
	global_store_dwordx4 v[54:55], v[34:37], off offset:256 nt
	s_waitcnt vmcnt(1)
	s_nop 0
	v_lshlrev_b32_e32 v34, 16, v38
	v_and_b32_e32 v35, 0xffff0000, v38
	v_lshlrev_b32_e32 v36, 16, v39
	v_and_b32_e32 v37, 0xffff0000, v39
	v_lshlrev_b32_e32 v38, 16, v40
	v_and_b32_e32 v39, 0xffff0000, v40
	v_lshlrev_b32_e32 v40, 16, v41
	v_and_b32_e32 v41, 0xffff0000, v41
	v_mul_f32_e32 v30, v30, v34
	v_mul_f32_e32 v31, v31, v35
	v_mul_f32_e32 v32, v32, v36
	v_mul_f32_e32 v33, v33, v37
	v_mul_f32_e32 v29, v29, v41
	v_mul_f32_e32 v34, v26, v38
	v_mul_f32_e32 v35, v27, v39
	v_mul_f32_e32 v36, v28, v40
	v_cvt_pk_bf16_f32 v26, v30, v31
	v_cvt_pk_bf16_f32 v27, v32, v33
	v_cvt_pk_bf16_f32 v28, v34, v35
	v_cvt_pk_bf16_f32 v29, v36, v29
	global_load_dwordx4 v[30:33], v[42:43], off
	v_lshlrev_b64 v[38:39], 11, v[50:51]
	v_add_u32_e32 v34, 0xb0, v134
	v_lshl_add_u64 v[38:39], s[14:15], 0, v[38:39]
	v_mad_i64_i32 v[36:37], s[26:27], v34, s82, v[136:137]
	v_lshl_add_u64 v[38:39], v[38:39], 0, v[130:131]
	v_lshl_add_u64 v[36:37], v[36:37], 0, s[38:39]
	global_store_dwordx4 v[38:39], v[26:29], off nt
	v_lshl_add_u64 v[40:41], v[36:37], 0, v[130:131]
	v_ashrrev_i32_e32 v35, 31, v34
	s_waitcnt vmcnt(1)
	v_lshlrev_b32_e32 v26, 16, v30
	v_and_b32_e32 v27, 0xffff0000, v30
	v_lshlrev_b32_e32 v28, 16, v31
	v_and_b32_e32 v29, 0xffff0000, v31
	v_lshlrev_b32_e32 v30, 16, v32
	v_and_b32_e32 v31, 0xffff0000, v32
	v_lshlrev_b32_e32 v32, 16, v33
	v_and_b32_e32 v33, 0xffff0000, v33
	v_mul_f32_e32 v22, v22, v26
	v_mul_f32_e32 v23, v23, v27
	v_mul_f32_e32 v24, v24, v28
	v_mul_f32_e32 v25, v25, v29
	v_mul_f32_e32 v21, v21, v33
	v_mul_f32_e32 v26, v18, v30
	v_mul_f32_e32 v27, v19, v31
	v_mul_f32_e32 v28, v20, v32
	v_cvt_pk_bf16_f32 v18, v22, v23
	v_cvt_pk_bf16_f32 v19, v24, v25
	v_cvt_pk_bf16_f32 v20, v26, v27
	v_cvt_pk_bf16_f32 v21, v28, v21
	global_load_dwordx4 v[22:25], v[40:41], off
	v_lshl_add_u64 v[26:27], v[36:37], 0, v[132:133]
	global_store_dwordx4 v[38:39], v[18:21], off offset:256 nt
	s_waitcnt vmcnt(1)
	s_nop 0
	v_lshlrev_b32_e32 v18, 16, v22
	v_and_b32_e32 v19, 0xffff0000, v22
	v_lshlrev_b32_e32 v20, 16, v23
	v_and_b32_e32 v21, 0xffff0000, v23
	v_lshlrev_b32_e32 v22, 16, v24
	v_and_b32_e32 v23, 0xffff0000, v24
	v_lshlrev_b32_e32 v24, 16, v25
	v_and_b32_e32 v25, 0xffff0000, v25
	v_mul_f32_e32 v14, v14, v18
	v_mul_f32_e32 v15, v15, v19
	v_mul_f32_e32 v16, v16, v20
	v_mul_f32_e32 v17, v17, v21
	v_mul_f32_e32 v13, v13, v25
	v_mul_f32_e32 v18, v10, v22
	v_mul_f32_e32 v19, v11, v23
	v_mul_f32_e32 v20, v12, v24
	v_cvt_pk_bf16_f32 v10, v14, v15
	v_cvt_pk_bf16_f32 v11, v16, v17
	v_cvt_pk_bf16_f32 v12, v18, v19
	v_cvt_pk_bf16_f32 v13, v20, v13
	global_load_dwordx4 v[14:17], v[26:27], off
	v_lshlrev_b64 v[18:19], 11, v[34:35]
	v_lshl_add_u64 v[18:19], s[14:15], 0, v[18:19]
	v_lshl_add_u64 v[18:19], v[18:19], 0, v[130:131]
	global_store_dwordx4 v[18:19], v[10:13], off nt
	s_waitcnt vmcnt(1)
	s_nop 0
	v_lshlrev_b32_e32 v10, 16, v14
	v_and_b32_e32 v11, 0xffff0000, v14
	v_lshlrev_b32_e32 v12, 16, v15
	v_and_b32_e32 v13, 0xffff0000, v15
	v_lshlrev_b32_e32 v14, 16, v16
	v_and_b32_e32 v15, 0xffff0000, v16
	v_lshlrev_b32_e32 v16, 16, v17
	v_and_b32_e32 v17, 0xffff0000, v17
	v_mul_f32_e32 v5, v5, v17
	v_mul_f32_e32 v6, v6, v10
	v_mul_f32_e32 v7, v7, v11
	v_mul_f32_e32 v8, v8, v12
	v_mul_f32_e32 v9, v9, v13
	v_mul_f32_e32 v10, v2, v14
	v_mul_f32_e32 v11, v3, v15
	v_mul_f32_e32 v12, v4, v16
	v_cvt_pk_bf16_f32 v2, v6, v7
	v_cvt_pk_bf16_f32 v3, v8, v9
	v_cvt_pk_bf16_f32 v4, v10, v11
	v_cvt_pk_bf16_f32 v5, v12, v5
	global_store_dwordx4 v[18:19], v[2:5], off offset:256 nt
	s_cbranch_vccnz .LBB0_95
	s_andn2_b64 vcc, exec, s[6:7]
	s_cbranch_vccnz .LBB0_94
	s_barrier
	s_branch .LBB0_94

; __device__ __forceinline__ unsigned cvt_pk_bf16(float lo, float hi) { unsigned r; asm volatile("v_cvt_pk_bf16_f32 %0, %1, %2" : "=v"(r) : "v"(lo), "v"(hi)); return r; }
;     __device__ __forceinline__ void operator()(const f32x4 (&acc)[2][2][4][2], const pg8::Unit& u, int wr, int wc, int fr, int fq, LAS unsigned char*) const {
;     ...
;                 const int row = row0 + ai * 128 + m * 16; const size_t off = (size_t)row * DM + col0; float q = 0.f;
; #pragma unroll
;                 for (int bj = 0; bj < 2; ++bj)
; #pragma unroll
;                     for (int n = 0; n < 2; ++n) { const size_t o = off + bj * 128 + n * 16; const f32x4 xv = *(const f32x4*)(xin + o) + acc[ai][bj][m][n]; *(f32x4*)(xout + o) = xv;
;                         q += (xv[0] * xv[0] + xv[1] * xv[1]) + (xv[2] * xv[2] + xv[3] * xv[3]);
;                         u32x2 w; w.x = cvt_pk_bf16(xv[0], xv[1]); w.y = cvt_pk_bf16(xv[2], xv[3]); *(u32x2*)(xb + o) = w; }
;                 q += __shfl_xor(q, 16); q += __shfl_xor(q, 32);
;                 if (fq == 0) ssq[(size_t)row * 16 + u.pn * 4 + wc] = q;
.LBB0_421:
	v_lshl_add_u32 v136, s68, 8, v142
	v_lshl_or_b32 v137, s28, 8, v144
	s_lshl_b32 s50, s28, 4
	s_lshl_b32 s51, s59, 2
	s_add_u32 s50, s50, s51
	v_lshl_add_u32 v139, v136, 10, v137
	v_lshl_add_u32 v140, v136, 6, s50
	v_lshlrev_b32_e32 v138, 2, v139
	v_lshlrev_b32_e32 v139, 1, v139
	v_xor_b32_e32 v141, 16, v187
	v_xor_b32_e32 v172, 32, v187
	v_lshlrev_b32_e32 v141, 2, v141
	v_lshlrev_b32_e32 v172, 2, v172
	global_load_dwordx4 v[198:201], v138, s[12:13]
	global_load_dwordx4 v[202:205], v138, s[12:13] offset:64
	global_load_dwordx4 v[206:209], v138, s[12:13] offset:512
	global_load_dwordx4 v[210:213], v138, s[12:13] offset:576
	v_add_u32_e32 v173, 0x10000, v138
	global_load_dwordx4 v[214:217], v173, s[12:13]
	global_load_dwordx4 v[218:221], v173, s[12:13] offset:64
	global_load_dwordx4 v[222:225], v173, s[12:13] offset:512
	global_load_dwordx4 v[226:229], v173, s[12:13] offset:576
	v_add_u32_e32 v173, 0x20000, v138
	global_load_dwordx4 v[156:159], v173, s[12:13]
	global_load_dwordx4 v[160:163], v173, s[12:13] offset:64
	global_load_dwordx4 v[164:167], v173, s[12:13] offset:512
	global_load_dwordx4 v[168:171], v173, s[12:13] offset:576
	v_mov_b32_e32 v174, v138
	v_mov_b32_e32 v175, v139
	v_mov_b32_e32 v176, v140
	s_waitcnt vmcnt(11)
	v_pk_add_f32 v[200:201], v[128:129], v[200:201]
	v_pk_add_f32 v[198:199], v[126:127], v[198:199]
	global_store_dwordx4 v174, v[198:201], s[84:85] nt
	v_mul_f32_e32 v178, v201, v201
	v_mul_f32_e32 v177, v199, v199
	v_fmac_f32_e32 v177, v198, v198
	v_fmac_f32_e32 v178, v200, v200
	v_cvt_pk_bf16_f32 v180, v198, v199
	v_cvt_pk_bf16_f32 v181, v200, v201
	v_add_f32_e32 v179, v177, v178
	global_store_dwordx2 v175, v[180:181], s[18:19] nt
	s_waitcnt vmcnt(12)
	v_pk_add_f32 v[204:205], v[124:125], v[204:205]
	v_pk_add_f32 v[202:203], v[122:123], v[202:203]
	global_store_dwordx4 v174, v[202:205], s[84:85] offset:64 nt
	v_mul_f32_e32 v178, v205, v205
	v_mul_f32_e32 v177, v203, v203
	v_fmac_f32_e32 v177, v202, v202
	v_fmac_f32_e32 v178, v204, v204
	v_cvt_pk_bf16_f32 v182, v202, v203
	v_cvt_pk_bf16_f32 v183, v204, v205
	v_add_f32_e32 v177, v177, v178
	v_add_f32_e32 v179, v179, v177
	global_store_dwordx2 v175, v[182:183], s[18:19] offset:32 nt
	s_waitcnt vmcnt(13)
	v_pk_add_f32 v[208:209], v[120:121], v[208:209]
	v_pk_add_f32 v[206:207], v[118:119], v[206:207]
	global_store_dwordx4 v174, v[206:209], s[84:85] offset:512 nt
	v_mul_f32_e32 v178, v209, v209
	v_mul_f32_e32 v177, v207, v207
	v_fmac_f32_e32 v177, v206, v206
	v_fmac_f32_e32 v178, v208, v208
	v_cvt_pk_bf16_f32 v180, v206, v207
	v_cvt_pk_bf16_f32 v181, v208, v209
	v_add_f32_e32 v177, v177, v178
	v_add_f32_e32 v179, v179, v177
	global_store_dwordx2 v175, v[180:181], s[18:19] offset:256 nt
	s_waitcnt vmcnt(14)
	v_pk_add_f32 v[212:213], v[116:117], v[212:213]
	v_pk_add_f32 v[210:211], v[114:115], v[210:211]
	global_store_dwordx4 v174, v[210:213], s[84:85] offset:576 nt
	v_mul_f32_e32 v178, v213, v213
	v_mul_f32_e32 v177, v211, v211
	v_fmac_f32_e32 v177, v210, v210
	v_fmac_f32_e32 v178, v212, v212
	v_cvt_pk_bf16_f32 v182, v210, v211
	v_cvt_pk_bf16_f32 v183, v212, v213
	v_add_f32_e32 v177, v177, v178
	v_add_f32_e32 v179, v179, v177
	global_store_dwordx2 v175, v[182:183], s[18:19] offset:288 nt
	ds_bpermute_b32 v177, v141, v179
	s_waitcnt lgkmcnt(0)
	v_add_f32_e32 v179, v179, v177
	ds_bpermute_b32 v178, v172, v179
	s_waitcnt lgkmcnt(0)
	v_add_f32_e32 v179, v179, v178
	s_and_saveexec_b64 s[52:53], s[4:5]
	global_store_dword v176, v179, s[14:15]
	s_mov_b64 exec, s[52:53]
	v_add_u32_e32 v173, 0x30000, v138
	global_load_dwordx4 v[198:201], v173, s[12:13]
	global_load_dwordx4 v[202:205], v173, s[12:13] offset:64
	global_load_dwordx4 v[206:209], v173, s[12:13] offset:512
	global_load_dwordx4 v[210:213], v173, s[12:13] offset:576
	v_add_u32_e32 v174, 0x10000, v138
	v_add_u32_e32 v175, 0x8000, v139
	v_add_u32_e32 v176, 0x400, v140
	s_waitcnt vmcnt(20)
	v_pk_add_f32 v[216:217], v[112:113], v[216:217]
	v_pk_add_f32 v[214:215], v[110:111], v[214:215]
	global_store_dwordx4 v174, v[214:217], s[84:85] nt
	v_mul_f32_e32 v178, v217, v217
	v_mul_f32_e32 v177, v215, v215
	v_fmac_f32_e32 v177, v214, v214
	v_fmac_f32_e32 v178, v216, v216
	v_cvt_pk_bf16_f32 v180, v214, v215
	v_cvt_pk_bf16_f32 v181, v216, v217
	v_add_f32_e32 v179, v177, v178
	global_store_dwordx2 v175, v[180:181], s[18:19] nt
	s_waitcnt vmcnt(21)
	v_pk_add_f32 v[220:221], v[108:109], v[220:221]
	v_pk_add_f32 v[218:219], v[106:107], v[218:219]
	global_store_dwordx4 v174, v[218:221], s[84:85] offset:64 nt
	v_mul_f32_e32 v178, v221, v221
	v_mul_f32_e32 v177, v219, v219
	v_fmac_f32_e32 v177, v218, v218
	v_fmac_f32_e32 v178, v220, v220
	v_cvt_pk_bf16_f32 v182, v218, v219
	v_cvt_pk_bf16_f32 v183, v220, v221
	v_add_f32_e32 v177, v177, v178
	v_add_f32_e32 v179, v179, v177
	global_store_dwordx2 v175, v[182:183], s[18:19] offset:32 nt
	s_waitcnt vmcnt(22)
	v_pk_add_f32 v[224:225], v[104:105], v[224:225]
	v_pk_add_f32 v[222:223], v[102:103], v[222:223]
	global_store_dwordx4 v174, v[222:225], s[84:85] offset:512 nt
	v_mul_f32_e32 v178, v225, v225
	v_mul_f32_e32 v177, v223, v223
	v_fmac_f32_e32 v177, v222, v222
	v_fmac_f32_e32 v178, v224, v224
	v_cvt_pk_bf16_f32 v180, v222, v223
	v_cvt_pk_bf16_f32 v181, v224, v225
	v_add_f32_e32 v177, v177, v178
	v_add_f32_e32 v179, v179, v177
	global_store_dwordx2 v175, v[180:181], s[18:19] offset:256 nt
	s_waitcnt vmcnt(23)
	v_pk_add_f32 v[228:229], v[100:101], v[228:229]
	v_pk_add_f32 v[226:227], v[98:99], v[226:227]
	global_store_dwordx4 v174, v[226:229], s[84:85] offset:576 nt
	v_mul_f32_e32 v178, v229, v229
	v_mul_f32_e32 v177, v227, v227
	v_fmac_f32_e32 v177, v226, v226
	v_fmac_f32_e32 v178, v228, v228
	v_cvt_pk_bf16_f32 v182, v226, v227
	v_cvt_pk_bf16_f32 v183, v228, v229
	v_add_f32_e32 v177, v177, v178
	v_add_f32_e32 v179, v179, v177
	global_store_dwordx2 v175, v[182:183], s[18:19] offset:288 nt
	ds_bpermute_b32 v177, v141, v179
	s_waitcnt lgkmcnt(0)
; __device__ __forceinline__ unsigned cvt_pk_bf16(float lo, float hi) { unsigned r; asm volatile("v_cvt_pk_bf16_f32 %0, %1, %2" : "=v"(r) : "v"(lo), "v"(hi)); return r; }
;     __device__ __forceinline__ void operator()(const f32x4 (&acc)[2][2][4][2], const pg8::Unit& u, int wr, int wc, int fr, int fq, LAS unsigned char*) const {
;     ...
;                 const int row = row0 + ai * 128 + m * 16; const size_t off = (size_t)row * DM + col0; float q = 0.f;
; #pragma unroll
;                 for (int bj = 0; bj < 2; ++bj)
; #pragma unroll
;                     for (int n = 0; n < 2; ++n) { const size_t o = off + bj * 128 + n * 16; const f32x4 xv = *(const f32x4*)(xin + o) + acc[ai][bj][m][n]; *(f32x4*)(xout + o) = xv;
;                         q += (xv[0] * xv[0] + xv[1] * xv[1]) + (xv[2] * xv[2] + xv[3] * xv[3]);
;                         u32x2 w; w.x = cvt_pk_bf16(xv[0], xv[1]); w.y = cvt_pk_bf16(xv[2], xv[3]); *(u32x2*)(xb + o) = w; }
;                 q += __shfl_xor(q, 16); q += __shfl_xor(q, 32);
;                 if (fq == 0) ssq[(size_t)row * 16 + u.pn * 4 + wc] = q;
	v_add_f32_e32 v179, v179, v177
	ds_bpermute_b32 v178, v172, v179
	s_waitcnt lgkmcnt(0)
	v_add_f32_e32 v179, v179, v178
	s_and_saveexec_b64 s[52:53], s[4:5]
	global_store_dword v176, v179, s[14:15]
	s_mov_b64 exec, s[52:53]
	v_add_u32_e32 v173, 0x80000, v138
	global_load_dwordx4 v[214:217], v173, s[12:13]
	global_load_dwordx4 v[218:221], v173, s[12:13] offset:64
	global_load_dwordx4 v[222:225], v173, s[12:13] offset:512
	global_load_dwordx4 v[226:229], v173, s[12:13] offset:576
	v_add_u32_e32 v174, 0x20000, v138
	v_add_u32_e32 v175, 0x10000, v139
	v_add_u32_e32 v176, 0x800, v140
	s_waitcnt vmcnt(29)
	v_pk_add_f32 v[158:159], v[96:97], v[158:159]
	v_pk_add_f32 v[156:157], v[94:95], v[156:157]
	global_store_dwordx4 v174, v[156:159], s[84:85] nt
	v_mul_f32_e32 v178, v159, v159
	v_mul_f32_e32 v177, v157, v157
	v_fmac_f32_e32 v177, v156, v156
	v_fmac_f32_e32 v178, v158, v158
	v_cvt_pk_bf16_f32 v180, v156, v157
	v_cvt_pk_bf16_f32 v181, v158, v159
	v_add_f32_e32 v179, v177, v178
	global_store_dwordx2 v175, v[180:181], s[18:19] nt
	s_waitcnt vmcnt(30)
	v_pk_add_f32 v[162:163], v[92:93], v[162:163]
	v_pk_add_f32 v[160:161], v[90:91], v[160:161]
	global_store_dwordx4 v174, v[160:163], s[84:85] offset:64 nt
	v_mul_f32_e32 v178, v163, v163
	v_mul_f32_e32 v177, v161, v161
	v_fmac_f32_e32 v177, v160, v160
	v_fmac_f32_e32 v178, v162, v162
	v_cvt_pk_bf16_f32 v182, v160, v161
	v_cvt_pk_bf16_f32 v183, v162, v163
	v_add_f32_e32 v177, v177, v178
	v_add_f32_e32 v179, v179, v177
	global_store_dwordx2 v175, v[182:183], s[18:19] offset:32 nt
	s_waitcnt vmcnt(31)
	v_pk_add_f32 v[166:167], v[88:89], v[166:167]
	v_pk_add_f32 v[164:165], v[86:87], v[164:165]
	global_store_dwordx4 v174, v[164:167], s[84:85] offset:512 nt
	v_mul_f32_e32 v178, v167, v167
	v_mul_f32_e32 v177, v165, v165
	v_fmac_f32_e32 v177, v164, v164
	v_fmac_f32_e32 v178, v166, v166
	v_cvt_pk_bf16_f32 v180, v164, v165
	v_cvt_pk_bf16_f32 v181, v166, v167
	v_add_f32_e32 v177, v177, v178
	v_add_f32_e32 v179, v179, v177
	global_store_dwordx2 v175, v[180:181], s[18:19] offset:256 nt
	s_waitcnt vmcnt(32)
	v_pk_add_f32 v[170:171], v[84:85], v[170:171]
	v_pk_add_f32 v[168:169], v[82:83], v[168:169]
	global_store_dwordx4 v174, v[168:171], s[84:85] offset:576 nt
	v_mul_f32_e32 v178, v171, v171
	v_mul_f32_e32 v177, v169, v169
	v_fmac_f32_e32 v177, v168, v168
	v_fmac_f32_e32 v178, v170, v170
	v_cvt_pk_bf16_f32 v182, v168, v169
	v_cvt_pk_bf16_f32 v183, v170, v171
	v_add_f32_e32 v177, v177, v178
	v_add_f32_e32 v179, v179, v177
	global_store_dwordx2 v175, v[182:183], s[18:19] offset:288 nt
	ds_bpermute_b32 v177, v141, v179
	s_waitcnt lgkmcnt(0)
	v_add_f32_e32 v179, v179, v177
	ds_bpermute_b32 v178, v172, v179
	s_waitcnt lgkmcnt(0)
	v_add_f32_e32 v179, v179, v178
	s_and_saveexec_b64 s[52:53], s[4:5]
	global_store_dword v176, v179, s[14:15]
	s_mov_b64 exec, s[52:53]
	v_add_u32_e32 v173, 0x90000, v138
	global_load_dwordx4 v[156:159], v173, s[12:13]
	global_load_dwordx4 v[160:163], v173, s[12:13] offset:64
	global_load_dwordx4 v[164:167], v173, s[12:13] offset:512
	global_load_dwordx4 v[168:171], v173, s[12:13] offset:576
	v_add_u32_e32 v174, 0x30000, v138
	v_add_u32_e32 v175, 0x18000, v139
	v_add_u32_e32 v176, 0xc00, v140
	s_waitcnt vmcnt(29)
	v_pk_add_f32 v[200:201], v[80:81], v[200:201]
	v_pk_add_f32 v[198:199], v[78:79], v[198:199]
	global_store_dwordx4 v174, v[198:201], s[84:85] nt
	v_mul_f32_e32 v178, v201, v201
	v_mul_f32_e32 v177, v199, v199
	v_fmac_f32_e32 v177, v198, v198
	v_fmac_f32_e32 v178, v200, v200
	v_cvt_pk_bf16_f32 v180, v198, v199
	v_cvt_pk_bf16_f32 v181, v200, v201
	v_add_f32_e32 v179, v177, v178
	global_store_dwordx2 v175, v[180:181], s[18:19] nt
	s_waitcnt vmcnt(30)
	v_pk_add_f32 v[204:205], v[76:77], v[204:205]
	v_pk_add_f32 v[202:203], v[74:75], v[202:203]
	global_store_dwordx4 v174, v[202:205], s[84:85] offset:64 nt
	v_mul_f32_e32 v178, v205, v205
	v_mul_f32_e32 v177, v203, v203
	v_fmac_f32_e32 v177, v202, v202
	v_fmac_f32_e32 v178, v204, v204
	v_cvt_pk_bf16_f32 v182, v202, v203
	v_cvt_pk_bf16_f32 v183, v204, v205
	v_add_f32_e32 v177, v177, v178
	v_add_f32_e32 v179, v179, v177
	global_store_dwordx2 v175, v[182:183], s[18:19] offset:32 nt
	s_waitcnt vmcnt(31)
	v_pk_add_f32 v[208:209], v[72:73], v[208:209]
	v_pk_add_f32 v[206:207], v[70:71], v[206:207]
	global_store_dwordx4 v174, v[206:209], s[84:85] offset:512 nt
	v_mul_f32_e32 v178, v209, v209
	v_mul_f32_e32 v177, v207, v207
	v_fmac_f32_e32 v177, v206, v206
	v_fmac_f32_e32 v178, v208, v208
	v_cvt_pk_bf16_f32 v180, v206, v207
	v_cvt_pk_bf16_f32 v181, v208, v209
	v_add_f32_e32 v177, v177, v178
	v_add_f32_e32 v179, v179, v177
	global_store_dwordx2 v175, v[180:181], s[18:19] offset:256 nt
	s_waitcnt vmcnt(32)
	v_pk_add_f32 v[212:213], v[68:69], v[212:213]
	v_pk_add_f32 v[210:211], v[66:67], v[210:211]
	global_store_dwordx4 v174, v[210:213], s[84:85] offset:576 nt
	v_mul_f32_e32 v178, v213, v213
	v_mul_f32_e32 v177, v211, v211
	v_fmac_f32_e32 v177, v210, v210
	v_fmac_f32_e32 v178, v212, v212
	v_cvt_pk_bf16_f32 v182, v210, v211
	v_cvt_pk_bf16_f32 v183, v212, v213
	v_add_f32_e32 v177, v177, v178
	v_add_f32_e32 v179, v179, v177
	global_store_dwordx2 v175, v[182:183], s[18:19] offset:288 nt
	ds_bpermute_b32 v177, v141, v179
	s_waitcnt lgkmcnt(0)
	v_add_f32_e32 v179, v179, v177
	ds_bpermute_b32 v178, v172, v179
	s_waitcnt lgkmcnt(0)
	v_add_f32_e32 v179, v179, v178
	s_and_saveexec_b64 s[52:53], s[4:5]
	global_store_dword v176, v179, s[14:15]
	s_mov_b64 exec, s[52:53]
	v_add_u32_e32 v173, 0xa0000, v138
	global_load_dwordx4 v[198:201], v173, s[12:13]
	global_load_dwordx4 v[202:205], v173, s[12:13] offset:64
	global_load_dwordx4 v[206:209], v173, s[12:13] offset:512
	global_load_dwordx4 v[210:213], v173, s[12:13] offset:576
	v_add_u32_e32 v174, 0x80000, v138
	v_add_u32_e32 v175, 0x40000, v139
	v_add_u32_e32 v176, 0x2000, v140
	s_waitcnt vmcnt(29)
; __device__ __forceinline__ unsigned cvt_pk_bf16(float lo, float hi) { unsigned r; asm volatile("v_cvt_pk_bf16_f32 %0, %1, %2" : "=v"(r) : "v"(lo), "v"(hi)); return r; }
;     __device__ __forceinline__ void operator()(const f32x4 (&acc)[2][2][4][2], const pg8::Unit& u, int wr, int wc, int fr, int fq, LAS unsigned char*) const {
;     ...
;                 const int row = row0 + ai * 128 + m * 16; const size_t off = (size_t)row * DM + col0; float q = 0.f;
; #pragma unroll
;                 for (int bj = 0; bj < 2; ++bj)
; #pragma unroll
;                     for (int n = 0; n < 2; ++n) { const size_t o = off + bj * 128 + n * 16; const f32x4 xv = *(const f32x4*)(xin + o) + acc[ai][bj][m][n]; *(f32x4*)(xout + o) = xv;
;                         q += (xv[0] * xv[0] + xv[1] * xv[1]) + (xv[2] * xv[2] + xv[3] * xv[3]);
;                         u32x2 w; w.x = cvt_pk_bf16(xv[0], xv[1]); w.y = cvt_pk_bf16(xv[2], xv[3]); *(u32x2*)(xb + o) = w; }
;                 q += __shfl_xor(q, 16); q += __shfl_xor(q, 32);
;                 if (fq == 0) ssq[(size_t)row * 16 + u.pn * 4 + wc] = q;
	v_pk_add_f32 v[216:217], v[64:65], v[216:217]
	v_pk_add_f32 v[214:215], v[62:63], v[214:215]
	global_store_dwordx4 v174, v[214:217], s[84:85] nt
	v_mul_f32_e32 v178, v217, v217
	v_mul_f32_e32 v177, v215, v215
	v_fmac_f32_e32 v177, v214, v214
	v_fmac_f32_e32 v178, v216, v216
	v_cvt_pk_bf16_f32 v180, v214, v215
	v_cvt_pk_bf16_f32 v181, v216, v217
	v_add_f32_e32 v179, v177, v178
	global_store_dwordx2 v175, v[180:181], s[18:19] nt
	s_waitcnt vmcnt(30)
	v_pk_add_f32 v[220:221], v[60:61], v[220:221]
	v_pk_add_f32 v[218:219], v[58:59], v[218:219]
	global_store_dwordx4 v174, v[218:221], s[84:85] offset:64 nt
	v_mul_f32_e32 v178, v221, v221
	v_mul_f32_e32 v177, v219, v219
	v_fmac_f32_e32 v177, v218, v218
	v_fmac_f32_e32 v178, v220, v220
	v_cvt_pk_bf16_f32 v182, v218, v219
	v_cvt_pk_bf16_f32 v183, v220, v221
	v_add_f32_e32 v177, v177, v178
	v_add_f32_e32 v179, v179, v177
	global_store_dwordx2 v175, v[182:183], s[18:19] offset:32 nt
	s_waitcnt vmcnt(31)
	v_pk_add_f32 v[224:225], v[56:57], v[224:225]
	v_pk_add_f32 v[222:223], v[54:55], v[222:223]
	global_store_dwordx4 v174, v[222:225], s[84:85] offset:512 nt
	v_mul_f32_e32 v178, v225, v225
	v_mul_f32_e32 v177, v223, v223
	v_fmac_f32_e32 v177, v222, v222
	v_fmac_f32_e32 v178, v224, v224
	v_cvt_pk_bf16_f32 v180, v222, v223
	v_cvt_pk_bf16_f32 v181, v224, v225
	v_add_f32_e32 v177, v177, v178
	v_add_f32_e32 v179, v179, v177
	global_store_dwordx2 v175, v[180:181], s[18:19] offset:256 nt
	s_waitcnt vmcnt(32)
	v_pk_add_f32 v[228:229], v[52:53], v[228:229]
	v_pk_add_f32 v[226:227], v[50:51], v[226:227]
	global_store_dwordx4 v174, v[226:229], s[84:85] offset:576 nt
	v_mul_f32_e32 v178, v229, v229
	v_mul_f32_e32 v177, v227, v227
	v_fmac_f32_e32 v177, v226, v226
	v_fmac_f32_e32 v178, v228, v228
	v_cvt_pk_bf16_f32 v182, v226, v227
	v_cvt_pk_bf16_f32 v183, v228, v229
	v_add_f32_e32 v177, v177, v178
	v_add_f32_e32 v179, v179, v177
	global_store_dwordx2 v175, v[182:183], s[18:19] offset:288 nt
	ds_bpermute_b32 v177, v141, v179
	s_waitcnt lgkmcnt(0)
	v_add_f32_e32 v179, v179, v177
	ds_bpermute_b32 v178, v172, v179
	s_waitcnt lgkmcnt(0)
	v_add_f32_e32 v179, v179, v178
	s_and_saveexec_b64 s[52:53], s[4:5]
	global_store_dword v176, v179, s[14:15]
	s_mov_b64 exec, s[52:53]
	v_add_u32_e32 v173, 0xb0000, v138
	global_load_dwordx4 v[214:217], v173, s[12:13]
	global_load_dwordx4 v[218:221], v173, s[12:13] offset:64
	global_load_dwordx4 v[222:225], v173, s[12:13] offset:512
	global_load_dwordx4 v[226:229], v173, s[12:13] offset:576
	v_add_u32_e32 v174, 0x90000, v138
	v_add_u32_e32 v175, 0x48000, v139
	v_add_u32_e32 v176, 0x2400, v140
	s_waitcnt vmcnt(29)
	v_pk_add_f32 v[158:159], v[48:49], v[158:159]
	v_pk_add_f32 v[156:157], v[46:47], v[156:157]
	global_store_dwordx4 v174, v[156:159], s[84:85] nt
	v_mul_f32_e32 v178, v159, v159
	v_mul_f32_e32 v177, v157, v157
	v_fmac_f32_e32 v177, v156, v156
	v_fmac_f32_e32 v178, v158, v158
	v_cvt_pk_bf16_f32 v180, v156, v157
	v_cvt_pk_bf16_f32 v181, v158, v159
	v_add_f32_e32 v179, v177, v178
	global_store_dwordx2 v175, v[180:181], s[18:19] nt
	s_waitcnt vmcnt(30)
	v_pk_add_f32 v[162:163], v[44:45], v[162:163]
	v_pk_add_f32 v[160:161], v[42:43], v[160:161]
	global_store_dwordx4 v174, v[160:163], s[84:85] offset:64 nt
	v_mul_f32_e32 v178, v163, v163
	v_mul_f32_e32 v177, v161, v161
	v_fmac_f32_e32 v177, v160, v160
	v_fmac_f32_e32 v178, v162, v162
	v_cvt_pk_bf16_f32 v182, v160, v161
	v_cvt_pk_bf16_f32 v183, v162, v163
	v_add_f32_e32 v177, v177, v178
	v_add_f32_e32 v179, v179, v177
	global_store_dwordx2 v175, v[182:183], s[18:19] offset:32 nt
	s_waitcnt vmcnt(31)
	v_pk_add_f32 v[166:167], v[40:41], v[166:167]
	v_pk_add_f32 v[164:165], v[38:39], v[164:165]
	global_store_dwordx4 v174, v[164:167], s[84:85] offset:512 nt
	v_mul_f32_e32 v178, v167, v167
	v_mul_f32_e32 v177, v165, v165
	v_fmac_f32_e32 v177, v164, v164
	v_fmac_f32_e32 v178, v166, v166
	v_cvt_pk_bf16_f32 v180, v164, v165
	v_cvt_pk_bf16_f32 v181, v166, v167
	v_add_f32_e32 v177, v177, v178
	v_add_f32_e32 v179, v179, v177
	global_store_dwordx2 v175, v[180:181], s[18:19] offset:256 nt
	s_waitcnt vmcnt(32)
	v_pk_add_f32 v[170:171], v[36:37], v[170:171]
	v_pk_add_f32 v[168:169], v[34:35], v[168:169]
	global_store_dwordx4 v174, v[168:171], s[84:85] offset:576 nt
	v_mul_f32_e32 v178, v171, v171
	v_mul_f32_e32 v177, v169, v169
	v_fmac_f32_e32 v177, v168, v168
	v_fmac_f32_e32 v178, v170, v170
	v_cvt_pk_bf16_f32 v182, v168, v169
	v_cvt_pk_bf16_f32 v183, v170, v171
	v_add_f32_e32 v177, v177, v178
	v_add_f32_e32 v179, v179, v177
	global_store_dwordx2 v175, v[182:183], s[18:19] offset:288 nt
	ds_bpermute_b32 v177, v141, v179
	s_waitcnt lgkmcnt(0)
	v_add_f32_e32 v179, v179, v177
	ds_bpermute_b32 v178, v172, v179
	s_waitcnt lgkmcnt(0)
	v_add_f32_e32 v179, v179, v178
	s_and_saveexec_b64 s[52:53], s[4:5]
	global_store_dword v176, v179, s[14:15]
	s_mov_b64 exec, s[52:53]
	v_add_u32_e32 v174, 0xa0000, v138
	v_add_u32_e32 v175, 0x50000, v139
	v_add_u32_e32 v176, 0x2800, v140
	s_waitcnt vmcnt(25)
; __device__ __forceinline__ unsigned cvt_pk_bf16(float lo, float hi) { unsigned r; asm volatile("v_cvt_pk_bf16_f32 %0, %1, %2" : "=v"(r) : "v"(lo), "v"(hi)); return r; }
;     __device__ __forceinline__ void operator()(const f32x4 (&acc)[2][2][4][2], const pg8::Unit& u, int wr, int wc, int fr, int fq, LAS unsigned char*) const {
;     ...
;                 const int row = row0 + ai * 128 + m * 16; const size_t off = (size_t)row * DM + col0; float q = 0.f;
; #pragma unroll
;                 for (int bj = 0; bj < 2; ++bj)
; #pragma unroll
;                     for (int n = 0; n < 2; ++n) { const size_t o = off + bj * 128 + n * 16; const f32x4 xv = *(const f32x4*)(xin + o) + acc[ai][bj][m][n]; *(f32x4*)(xout + o) = xv;
;                         q += (xv[0] * xv[0] + xv[1] * xv[1]) + (xv[2] * xv[2] + xv[3] * xv[3]);
;                         u32x2 w; w.x = cvt_pk_bf16(xv[0], xv[1]); w.y = cvt_pk_bf16(xv[2], xv[3]); *(u32x2*)(xb + o) = w; }
;                 q += __shfl_xor(q, 16); q += __shfl_xor(q, 32);
;                 if (fq == 0) ssq[(size_t)row * 16 + u.pn * 4 + wc] = q;
	v_pk_add_f32 v[200:201], v[32:33], v[200:201]
	v_pk_add_f32 v[198:199], v[30:31], v[198:199]
	global_store_dwordx4 v174, v[198:201], s[84:85] nt
	v_mul_f32_e32 v178, v201, v201
	v_mul_f32_e32 v177, v199, v199
	v_fmac_f32_e32 v177, v198, v198
	v_fmac_f32_e32 v178, v200, v200
	v_cvt_pk_bf16_f32 v180, v198, v199
	v_cvt_pk_bf16_f32 v181, v200, v201
	v_add_f32_e32 v179, v177, v178
	global_store_dwordx2 v175, v[180:181], s[18:19] nt
	s_waitcnt vmcnt(26)
	v_pk_add_f32 v[204:205], v[28:29], v[204:205]
	v_pk_add_f32 v[202:203], v[26:27], v[202:203]
	global_store_dwordx4 v174, v[202:205], s[84:85] offset:64 nt
	v_mul_f32_e32 v178, v205, v205
	v_mul_f32_e32 v177, v203, v203
	v_fmac_f32_e32 v177, v202, v202
	v_fmac_f32_e32 v178, v204, v204
	v_cvt_pk_bf16_f32 v182, v202, v203
	v_cvt_pk_bf16_f32 v183, v204, v205
	v_add_f32_e32 v177, v177, v178
	v_add_f32_e32 v179, v179, v177
	global_store_dwordx2 v175, v[182:183], s[18:19] offset:32 nt
	s_waitcnt vmcnt(27)
	v_pk_add_f32 v[208:209], v[24:25], v[208:209]
	v_pk_add_f32 v[206:207], v[22:23], v[206:207]
	global_store_dwordx4 v174, v[206:209], s[84:85] offset:512 nt
	v_mul_f32_e32 v178, v209, v209
	v_mul_f32_e32 v177, v207, v207
	v_fmac_f32_e32 v177, v206, v206
	v_fmac_f32_e32 v178, v208, v208
	v_cvt_pk_bf16_f32 v180, v206, v207
	v_cvt_pk_bf16_f32 v181, v208, v209
	v_add_f32_e32 v177, v177, v178
	v_add_f32_e32 v179, v179, v177
	global_store_dwordx2 v175, v[180:181], s[18:19] offset:256 nt
	s_waitcnt vmcnt(28)
	v_pk_add_f32 v[212:213], v[20:21], v[212:213]
	v_pk_add_f32 v[210:211], v[18:19], v[210:211]
	global_store_dwordx4 v174, v[210:213], s[84:85] offset:576 nt
	v_mul_f32_e32 v178, v213, v213
	v_mul_f32_e32 v177, v211, v211
	v_fmac_f32_e32 v177, v210, v210
	v_fmac_f32_e32 v178, v212, v212
	v_cvt_pk_bf16_f32 v182, v210, v211
	v_cvt_pk_bf16_f32 v183, v212, v213
	v_add_f32_e32 v177, v177, v178
	v_add_f32_e32 v179, v179, v177
	global_store_dwordx2 v175, v[182:183], s[18:19] offset:288 nt
	ds_bpermute_b32 v177, v141, v179
	s_waitcnt lgkmcnt(0)
	v_add_f32_e32 v179, v179, v177
	ds_bpermute_b32 v178, v172, v179
	s_waitcnt lgkmcnt(0)
	v_add_f32_e32 v179, v179, v178
	s_and_saveexec_b64 s[52:53], s[4:5]
	global_store_dword v176, v179, s[14:15]
	s_mov_b64 exec, s[52:53]
	v_add_u32_e32 v174, 0xb0000, v138
	v_add_u32_e32 v175, 0x58000, v139
	v_add_u32_e32 v176, 0x2c00, v140
	s_waitcnt vmcnt(21)
	v_pk_add_f32 v[216:217], v[16:17], v[216:217]
	v_pk_add_f32 v[214:215], v[14:15], v[214:215]
	global_store_dwordx4 v174, v[214:217], s[84:85] nt
	v_mul_f32_e32 v178, v217, v217
	v_mul_f32_e32 v177, v215, v215
	v_fmac_f32_e32 v177, v214, v214
	v_fmac_f32_e32 v178, v216, v216
	v_cvt_pk_bf16_f32 v180, v214, v215
	v_cvt_pk_bf16_f32 v181, v216, v217
	v_add_f32_e32 v179, v177, v178
	global_store_dwordx2 v175, v[180:181], s[18:19] nt
	s_waitcnt vmcnt(22)
	v_pk_add_f32 v[220:221], v[12:13], v[220:221]
	v_pk_add_f32 v[218:219], v[10:11], v[218:219]
	global_store_dwordx4 v174, v[218:221], s[84:85] offset:64 nt
	v_mul_f32_e32 v178, v221, v221
	v_mul_f32_e32 v177, v219, v219
	v_fmac_f32_e32 v177, v218, v218
	v_fmac_f32_e32 v178, v220, v220
	v_cvt_pk_bf16_f32 v182, v218, v219
	v_cvt_pk_bf16_f32 v183, v220, v221
	v_add_f32_e32 v177, v177, v178
	v_add_f32_e32 v179, v179, v177
	global_store_dwordx2 v175, v[182:183], s[18:19] offset:32 nt
	s_waitcnt vmcnt(23)
	v_pk_add_f32 v[224:225], v[8:9], v[224:225]
	v_pk_add_f32 v[222:223], v[6:7], v[222:223]
	global_store_dwordx4 v174, v[222:225], s[84:85] offset:512 nt
	v_mul_f32_e32 v178, v225, v225
	v_mul_f32_e32 v177, v223, v223
	v_fmac_f32_e32 v177, v222, v222
	v_fmac_f32_e32 v178, v224, v224
	v_cvt_pk_bf16_f32 v180, v222, v223
	v_cvt_pk_bf16_f32 v181, v224, v225
	v_add_f32_e32 v177, v177, v178
	v_add_f32_e32 v179, v179, v177
	global_store_dwordx2 v175, v[180:181], s[18:19] offset:256 nt
	s_waitcnt vmcnt(24)
	v_pk_add_f32 v[228:229], v[4:5], v[228:229]
	v_pk_add_f32 v[226:227], v[2:3], v[226:227]
	global_store_dwordx4 v174, v[226:229], s[84:85] offset:576 nt
	v_mul_f32_e32 v178, v229, v229
	v_mul_f32_e32 v177, v227, v227
	v_fmac_f32_e32 v177, v226, v226
	v_fmac_f32_e32 v178, v228, v228
	v_cvt_pk_bf16_f32 v182, v226, v227
	v_cvt_pk_bf16_f32 v183, v228, v229
	v_add_f32_e32 v177, v177, v178
	v_add_f32_e32 v179, v179, v177
	global_store_dwordx2 v175, v[182:183], s[18:19] offset:288 nt
	ds_bpermute_b32 v177, v141, v179
	s_waitcnt lgkmcnt(0)
	v_add_f32_e32 v179, v179, v177
	ds_bpermute_b32 v178, v172, v179
	s_waitcnt lgkmcnt(0)
	v_add_f32_e32 v179, v179, v178
	s_and_saveexec_b64 s[52:53], s[4:5]
	global_store_dword v176, v179, s[14:15]
	s_mov_b64 exec, s[52:53]
	s_and_b64 vcc, exec, s[6:7]
	s_mov_b64 s[6:7], -1
	s_cbranch_vccnz .LBB0_406
	s_andn2_b64 vcc, exec, s[16:17]
	s_cbranch_vccnz .LBB0_405
	s_barrier
	s_branch .LBB0_405
